# P3/P4: state and operand loads without the nt hint
# speedup vs baseline: 1.0041x; 1.0041x over previous
.LBB0_539:
	v_add_u32_e32 v0, s3, v213
	v_add_u32_e32 v12, 0x200, v0
	v_cmp_le_i32_e32 vcc, s62, v12
	s_and_saveexec_b64 s[56:57], vcc
	s_xor_b64 s[56:57], exec, s[56:57]
	s_cbranch_execz .LBB0_546
	v_cmp_gt_i32_e32 vcc, s62, v0
	s_and_saveexec_b64 s[58:59], vcc
	s_cbranch_execz .LBB0_545
	v_mul_hi_i32 v1, v0, s64
	v_lshrrev_b32_e32 v2, 31, v1
	v_ashrrev_i32_e32 v1, 11, v1
	v_add_u32_e32 v1, v1, v2
	v_mul_i32_i24_e32 v2, 0x2400, v1
	v_sub_u32_e32 v0, v0, v2
	v_bfe_i32 v3, v0, 6, 16
	v_mul_i32_i24_e32 v3, 0x2aab, v3
	v_lshrrev_b32_e32 v4, 31, v3
	v_lshrrev_b32_e32 v3, 17, v3
	v_add_u16_e32 v3, v3, v4
	v_lshrrev_b32_e32 v2, 6, v0
	v_mul_lo_u16_e32 v3, 12, v3
	v_and_b32_e32 v108, 3, v1
	v_sub_u16_e32 v2, v2, v3
	v_lshrrev_b32_e32 v3, 2, v0
	v_lshlrev_b32_e32 v1, 4, v1
	v_bfe_i32 v2, v2, 0, 16
	v_and_b32_e32 v3, 8, v3
	v_and_b32_e32 v110, 0xffffffc0, v1
	v_lshl_or_b32 v2, v2, 4, v3
	v_or_b32_e32 v24, 2, v110
	v_ashrrev_i32_e32 v1, 31, v0
	v_ashrrev_i32_e32 v3, 31, v2
	v_ashrrev_i32_e32 v25, 31, v24
	v_lshlrev_b64 v[36:37], 4, v[0:1]
	v_lshlrev_b64 v[38:39], 2, v[2:3]
	v_lshlrev_b64 v[24:25], 2, v[24:25]
	v_lshl_add_u64 v[112:113], s[8:9], 0, v[36:37]
	v_lshl_add_u64 v[114:115], s[10:11], 0, v[38:39]
	v_or_b32_e32 v24, v24, v108
	v_or_b32_e32 v10, 1, v110
	v_mad_u64_u32 v[26:27], s[60:61], v24, s63, v[112:113]
	v_mad_u64_u32 v[28:29], s[60:61], v24, s65, v[114:115]
	v_or_b32_e32 v24, 3, v110
	v_ashrrev_i32_e32 v111, 31, v110
	v_ashrrev_i32_e32 v11, 31, v10
	v_mad_i32_i24 v27, v25, s63, v27
	v_mad_i32_i24 v29, v25, s65, v29
	v_ashrrev_i32_e32 v25, 31, v24
	v_lshlrev_b64 v[0:1], 2, v[110:111]
	v_lshlrev_b64 v[16:17], 2, v[10:11]
	v_lshlrev_b64 v[24:25], 2, v[24:25]
	v_or_b32_e32 v0, v0, v108
	v_or_b32_e32 v16, v16, v108
	v_or_b32_e32 v24, v24, v108
	v_mad_u64_u32 v[2:3], s[60:61], v0, s63, v[112:113]
	v_mad_u64_u32 v[8:9], s[60:61], v0, s65, v[114:115]
	v_mad_u64_u32 v[12:13], s[60:61], v16, s63, v[112:113]
	v_mad_u64_u32 v[20:21], s[60:61], v16, s65, v[114:115]
	v_mad_u64_u32 v[30:31], s[60:61], v24, s63, v[112:113]
	v_mad_i32_i24 v3, v1, s63, v3
	v_mad_i32_i24 v9, v1, s65, v9
	v_mad_i32_i24 v13, v17, s63, v13
	v_mad_i32_i24 v21, v17, s65, v21
	v_mad_i32_i24 v31, v25, s63, v31
	global_load_dwordx4 v[0:3], v[2:3], off
	s_nop 0
	global_load_dwordx4 v[4:7], v[8:9], off offset:16
	s_nop 0
	global_load_dwordx4 v[8:11], v[8:9], off
	s_nop 0
	global_load_dwordx4 v[12:15], v[12:13], off
	s_nop 0
	global_load_dwordx4 v[16:19], v[20:21], off offset:16
	s_nop 0
	global_load_dwordx4 v[20:23], v[20:21], off
	s_nop 0
	global_load_dwordx4 v[32:35], v[28:29], off
	global_load_dwordx4 v[60:63], v[30:31], off
	v_mad_u64_u32 v[30:31], s[60:61], v24, s65, v[114:115]
	v_mad_i32_i24 v31, v25, s65, v31
	global_load_dwordx4 v[52:55], v[30:31], off offset:16
	global_load_dwordx4 v[64:67], v[30:31], off
	s_nop 0
	global_load_dwordx4 v[24:27], v[26:27], off
	s_nop 0
	global_load_dwordx4 v[28:31], v[28:29], off offset:16
	v_mad_i64_i32 v[40:41], s[60:61], v110, s66, 0
	v_mul_hi_u32_u24_e32 v42, 0x24000, v108
	v_mul_u32_u24_e32 v43, 0x24000, v108
	v_or_b32_e32 v41, v41, v42
	v_or_b32_e32 v40, v40, v43
	v_lshl_add_u64 v[116:117], v[40:41], 0, v[36:37]
	v_mad_i64_i32 v[36:37], s[60:61], v110, s67, 0
	v_mul_hi_u32_u24_e32 v40, 0x300, v108
	v_mul_u32_u24_e32 v41, 0x300, v108
	v_or_b32_e32 v37, v37, v40
	v_or_b32_e32 v36, v36, v41
	v_lshl_add_u64 v[118:119], v[36:37], 0, v[38:39]
	v_mov_b32_e32 v128, 0
	s_mov_b32 s79, 0
	v_mov_b32_e32 v129, v128
	v_mov_b32_e32 v122, v128
	v_mov_b32_e32 v123, v128
	v_mov_b32_e32 v124, v128
	v_mov_b32_e32 v125, v128
	v_mov_b32_e32 v126, v128
	v_mov_b32_e32 v127, v128
	s_waitcnt vmcnt(0)
	v_mov_b64_e32 v[36:37], v[60:61]
	v_mov_b64_e32 v[40:41], v[52:53]
	v_mov_b64_e32 v[44:45], v[64:65]
	v_mov_b64_e32 v[42:43], v[54:55]
	v_mov_b64_e32 v[46:47], v[66:67]
	v_mov_b64_e32 v[38:39], v[62:63]
	s_branch .LBB0_543

.LBB0_543:
	v_lshl_add_u64 v[120:121], s[42:43], 0, v[116:117]
	v_add_co_u32_e32 v48, vcc, s68, v120
	v_lshl_add_u64 v[68:69], s[42:43], 0, v[118:119]
	s_nop 0
	v_addc_co_u32_e32 v49, vcc, 0, v121, vcc
	v_add_co_u32_e32 v56, vcc, s69, v68
	v_lshl_add_u64 v[50:51], v[68:69], 0, s[14:15]
	s_nop 0
	v_addc_co_u32_e32 v57, vcc, 0, v69, vcc
	v_add_co_u32_e32 v58, vcc, s70, v120
	v_lshl_add_u64 v[70:71], v[68:69], 0, s[18:19]
	s_nop 0
	v_addc_co_u32_e32 v59, vcc, 0, v121, vcc
	global_load_dwordx4 v[72:75], v[48:49], off
	s_nop 0
	global_load_dwordx4 v[48:51], v[50:51], off offset:16
	s_nop 0
	global_load_dwordx4 v[96:99], v[56:57], off
	global_load_dwordx4 v[92:95], v[56:57], off offset:3072
	global_load_dwordx4 v[80:83], v[58:59], off
	s_nop 0
	global_load_dwordx4 v[56:59], v[70:71], off offset:16
	v_add_co_u32_e32 v70, vcc, s71, v120
	v_lshl_add_u64 v[76:77], v[68:69], 0, s[22:23]
	s_nop 0
	v_addc_co_u32_e32 v71, vcc, 0, v121, vcc
	v_add_co_u32_e32 v88, vcc, s72, v68
	global_load_dwordx4 v[84:87], v[70:71], off
	s_nop 0
	global_load_dwordx4 v[76:79], v[76:77], off offset:16
	v_addc_co_u32_e32 v89, vcc, 0, v69, vcc
	v_add_co_u32_e32 v70, vcc, s73, v120
	v_lshlrev_b32_e32 v134, 16, v0
	s_nop 0
	v_addc_co_u32_e32 v71, vcc, 0, v121, vcc
	global_load_dwordx4 v[100:103], v[88:89], off offset:2048
	s_nop 0
	global_load_dwordx4 v[88:91], v[70:71], off
	v_lshl_add_u64 v[70:71], v[68:69], 0, s[26:27]
	v_add_co_u32_e32 v68, vcc, s74, v68
	v_and_b32_e32 v135, 0xffff0000, v0
	s_nop 0
	v_addc_co_u32_e32 v69, vcc, 0, v69, vcc
	global_load_dwordx4 v[104:107], v[68:69], off offset:1024
	s_nop 0
	global_load_dwordx4 v[68:71], v[70:71], off offset:16
	v_cvt_pk_bf16_f32 v130, v122, v123
	v_lshlrev_b32_e32 v136, 16, v12
	v_and_b32_e32 v137, 0xffff0000, v12
	v_pk_fma_f32 v[122:123], v[122:123], v[8:9], v[134:135]
	v_cvt_pk_bf16_f32 v131, v124, v125
	v_cvt_pk_bf16_f32 v134, v122, v123
	v_pk_fma_f32 v[122:123], v[20:21], v[122:123], v[136:137]
	v_lshlrev_b32_e32 v136, 16, v1
	v_and_b32_e32 v137, 0xffff0000, v1
	v_lshlrev_b32_e32 v140, 16, v13
	v_and_b32_e32 v141, 0xffff0000, v13
	v_pk_fma_f32 v[124:125], v[124:125], v[10:11], v[136:137]
	v_lshlrev_b32_e32 v136, 16, v2
	v_and_b32_e32 v137, 0xffff0000, v2
	v_cvt_pk_bf16_f32 v132, v126, v127
	v_cvt_pk_bf16_f32 v135, v124, v125
	v_pk_fma_f32 v[124:125], v[22:23], v[124:125], v[140:141]
	v_lshlrev_b32_e32 v140, 16, v14
	v_and_b32_e32 v141, 0xffff0000, v14
	v_pk_fma_f32 v[126:127], v[126:127], v[4:5], v[136:137]
	v_lshlrev_b32_e32 v146, 16, v26
	v_and_b32_e32 v147, 0xffff0000, v26
	v_cvt_pk_bf16_f32 v136, v126, v127
	v_pk_fma_f32 v[150:151], v[16:17], v[126:127], v[140:141]
	v_lshlrev_b32_e32 v126, 16, v3
	v_and_b32_e32 v127, 0xffff0000, v3
	v_cvt_pk_bf16_f32 v133, v128, v129
	v_pk_fma_f32 v[126:127], v[128:129], v[6:7], v[126:127]
	v_pk_fma_f32 v[128:129], v[28:29], v[150:151], v[146:147]
	v_add_co_u32_e32 v146, vcc, s75, v120
	v_lshlrev_b32_e32 v152, 16, v15
	s_nop 0
	v_addc_co_u32_e32 v147, vcc, 0, v121, vcc
	global_store_dwordx4 v[146:147], v[130:133], off sc1
	v_and_b32_e32 v153, 0xffff0000, v15
	v_cvt_pk_bf16_f32 v137, v126, v127
	v_add_co_u32_e32 v130, vcc, s76, v120
	v_pk_fma_f32 v[152:153], v[18:19], v[126:127], v[152:153]
	s_nop 0
	v_addc_co_u32_e32 v131, vcc, 0, v121, vcc
	global_store_dwordx4 v[130:131], v[134:137], off sc1
	v_add_co_u32_e32 v130, vcc, 0x14924000, v120
	v_cvt_pk_bf16_f32 v138, v122, v123
	v_cvt_pk_bf16_f32 v139, v124, v125
	v_cvt_pk_bf16_f32 v140, v150, v151
	v_cvt_pk_bf16_f32 v141, v152, v153
	v_addc_co_u32_e32 v131, vcc, 0, v121, vcc
	v_lshlrev_b32_e32 v142, 16, v24
	v_and_b32_e32 v143, 0xffff0000, v24
	v_lshlrev_b32_e32 v144, 16, v25
	v_and_b32_e32 v145, 0xffff0000, v25
	v_lshlrev_b32_e32 v148, 16, v27
	v_and_b32_e32 v149, 0xffff0000, v27
	global_store_dwordx4 v[130:131], v[138:141], off sc1
	v_add_co_u32_e32 v130, vcc, 0x149b4000, v120
	s_cmp_gt_u32 s79, 55
	v_pk_fma_f32 v[126:127], v[32:33], v[122:123], v[142:143]
	v_pk_fma_f32 v[122:123], v[34:35], v[124:125], v[144:145]
	v_pk_fma_f32 v[124:125], v[30:31], v[152:153], v[148:149]
	v_addc_co_u32_e32 v131, vcc, 0, v121, vcc
	s_cselect_b64 s[60:61], -1, 0
	v_cvt_pk_bf16_f32 v142, v126, v127
	v_cvt_pk_bf16_f32 v143, v122, v123
	v_cvt_pk_bf16_f32 v144, v128, v129
	v_cvt_pk_bf16_f32 v145, v124, v125
	s_and_b64 vcc, exec, s[60:61]
	global_store_dwordx4 v[130:131], v[142:145], off sc1
	s_cbranch_vccnz .LBB0_542
	v_add_u32_e32 v34, s79, v110
	v_add_u32_e32 v0, 8, v34
	v_add_u32_e32 v10, 9, v34
	v_add_u32_e32 v24, 10, v34
	v_add_u32_e32 v34, 11, v34
	v_ashrrev_i32_e32 v1, 31, v0
	v_ashrrev_i32_e32 v11, 31, v10
	v_ashrrev_i32_e32 v25, 31, v24
	v_ashrrev_i32_e32 v35, 31, v34
	v_lshlrev_b64 v[0:1], 2, v[0:1]
	v_lshlrev_b64 v[16:17], 2, v[10:11]
	v_lshlrev_b64 v[24:25], 2, v[24:25]
	v_lshlrev_b64 v[40:41], 2, v[34:35]
	v_or_b32_e32 v0, v0, v108
	v_or_b32_e32 v16, v16, v108
	v_or_b32_e32 v24, v24, v108
	v_or_b32_e32 v40, v40, v108
	v_mad_u64_u32 v[2:3], s[80:81], v0, s63, v[112:113]
	v_mad_u64_u32 v[8:9], s[80:81], v0, s65, v[114:115]
	v_mad_u64_u32 v[12:13], s[80:81], v16, s63, v[112:113]
	v_mad_u64_u32 v[20:21], s[80:81], v16, s65, v[114:115]
	v_mad_u64_u32 v[26:27], s[80:81], v24, s63, v[112:113]
	v_mad_u64_u32 v[32:33], s[80:81], v24, s65, v[114:115]
	v_mad_u64_u32 v[36:37], s[80:81], v40, s63, v[112:113]
	v_mad_u64_u32 v[44:45], s[80:81], v40, s65, v[114:115]
	v_mad_i32_i24 v3, v1, s63, v3
	v_mad_i32_i24 v9, v1, s65, v9
	v_mad_i32_i24 v13, v17, s63, v13
	v_mad_i32_i24 v21, v17, s65, v21
	v_mad_i32_i24 v27, v25, s63, v27
	v_mad_i32_i24 v33, v25, s65, v33
	v_mad_i32_i24 v37, v41, s63, v37
	v_mad_i32_i24 v45, v41, s65, v45
	global_load_dwordx4 v[0:3], v[2:3], off
	s_nop 0
	global_load_dwordx4 v[4:7], v[8:9], off offset:16
	s_nop 0
	global_load_dwordx4 v[8:11], v[8:9], off
	s_nop 0
	global_load_dwordx4 v[12:15], v[12:13], off
	s_nop 0
	global_load_dwordx4 v[16:19], v[20:21], off offset:16
	s_nop 0
	global_load_dwordx4 v[20:23], v[20:21], off
	s_nop 0
	global_load_dwordx4 v[24:27], v[26:27], off
	s_nop 0
	global_load_dwordx4 v[28:31], v[32:33], off offset:16
	s_nop 0
	global_load_dwordx4 v[32:35], v[32:33], off
	s_nop 0
	global_load_dwordx4 v[36:39], v[36:37], off
	s_nop 0
	global_load_dwordx4 v[40:43], v[44:45], off offset:16
	s_nop 0
	global_load_dwordx4 v[44:47], v[44:45], off
	s_branch .LBB0_542

.LBB0_546:
	s_andn2_saveexec_b64 s[56:57], s[56:57]
	s_cbranch_execz .LBB0_538
	v_mul_hi_i32 v1, v0, s64
	v_lshrrev_b32_e32 v2, 31, v1
	v_ashrrev_i32_e32 v1, 11, v1
	v_add_u32_e32 v1, v1, v2
	v_mul_i32_i24_e32 v2, 0x2400, v1
	v_sub_u32_e32 v0, v0, v2
	v_bfe_i32 v3, v0, 6, 16
	v_mul_i32_i24_e32 v3, 0x2aab, v3
	v_lshrrev_b32_e32 v4, 31, v3
	v_lshrrev_b32_e32 v3, 17, v3
	v_add_u16_e32 v3, v3, v4
	v_lshrrev_b32_e32 v2, 6, v0
	v_mul_lo_u16_e32 v3, 12, v3
	v_and_b32_e32 v120, 3, v1
	v_sub_u16_e32 v2, v2, v3
	v_lshrrev_b32_e32 v3, 2, v0
	v_lshlrev_b32_e32 v1, 4, v1
	v_bfe_i32 v2, v2, 0, 16
	v_and_b32_e32 v3, 8, v3
	v_and_b32_e32 v122, 0xffffffc0, v1
	v_lshl_or_b32 v2, v2, 4, v3
	v_or_b32_e32 v10, 1, v122
	v_ashrrev_i32_e32 v1, 31, v0
	v_ashrrev_i32_e32 v3, 31, v2
	v_ashrrev_i32_e32 v123, 31, v122
	v_ashrrev_i32_e32 v11, 31, v10
	v_lshlrev_b64 v[36:37], 4, v[0:1]
	v_lshlrev_b64 v[38:39], 2, v[2:3]
	v_lshlrev_b64 v[0:1], 2, v[122:123]
	v_lshlrev_b64 v[14:15], 2, v[10:11]
	v_lshl_add_u64 v[124:125], s[8:9], 0, v[36:37]
	v_lshl_add_u64 v[126:127], s[10:11], 0, v[38:39]
	v_or_b32_e32 v0, v0, v120
	v_or_b32_e32 v13, v14, v120
	v_mad_u64_u32 v[2:3], s[58:59], v0, s63, v[124:125]
	v_mad_u64_u32 v[8:9], s[58:59], v0, s65, v[126:127]
	v_mad_u64_u32 v[16:17], s[58:59], v13, s63, v[124:125]
	v_mad_i32_i24 v3, v1, s63, v3
	v_mad_i32_i24 v9, v1, s65, v9
	v_mad_i32_i24 v17, v15, s63, v17
	global_load_dwordx4 v[0:3], v[2:3], off
	s_nop 0
	global_load_dwordx4 v[4:7], v[8:9], off offset:16
	s_nop 0
	global_load_dwordx4 v[8:11], v[8:9], off
	s_nop 0
	global_load_dwordx4 v[28:31], v[16:17], off
	v_mad_u64_u32 v[16:17], s[58:59], v13, s65, v[126:127]
	v_mul_hi_i32 v13, v12, s64
	v_lshrrev_b32_e32 v14, 31, v13
	v_ashrrev_i32_e32 v13, 11, v13
	v_add_u32_e32 v13, v13, v14
	v_mul_i32_i24_e32 v14, 0x2400, v13
	v_sub_u32_e32 v12, v12, v14
	v_mad_i32_i24 v17, v15, s65, v17
	v_bfe_i32 v15, v12, 6, 16
	v_mul_i32_i24_e32 v15, 0x2aab, v15
	global_load_dwordx4 v[24:27], v[16:17], off offset:16
	global_load_dwordx4 v[32:35], v[16:17], off
	v_lshrrev_b32_e32 v16, 31, v15
	v_lshrrev_b32_e32 v15, 17, v15
	v_add_u16_e32 v15, v15, v16
	v_lshrrev_b32_e32 v14, 6, v12
	v_mul_lo_u16_e32 v15, 12, v15
	v_sub_u16_e32 v14, v14, v15
	v_lshrrev_b32_e32 v15, 2, v12
	v_and_b32_e32 v128, 3, v13
	v_bfe_i32 v14, v14, 0, 16
	v_and_b32_e32 v15, 8, v15
	v_lshlrev_b32_e32 v13, 4, v13
	v_lshl_or_b32 v14, v14, 4, v15
	v_and_b32_e32 v130, 0xffffffc0, v13
	v_ashrrev_i32_e32 v13, 31, v12
	v_ashrrev_i32_e32 v15, 31, v14
	v_ashrrev_i32_e32 v131, 31, v130
	v_lshlrev_b64 v[40:41], 4, v[12:13]
	v_lshlrev_b64 v[42:43], 2, v[14:15]
	v_lshlrev_b64 v[12:13], 2, v[130:131]
	v_lshl_add_u64 v[132:133], s[8:9], 0, v[40:41]
	v_lshl_add_u64 v[134:135], s[10:11], 0, v[42:43]
	v_or_b32_e32 v12, v12, v128
	v_mad_u64_u32 v[14:15], s[58:59], v12, s63, v[132:133]
	v_mad_u64_u32 v[16:17], s[58:59], v12, s65, v[134:135]
	v_or_b32_e32 v12, 1, v130
	v_mad_i32_i24 v15, v13, s63, v15
	v_mad_i32_i24 v17, v13, s65, v17
	v_ashrrev_i32_e32 v13, 31, v12
	v_lshlrev_b64 v[12:13], 2, v[12:13]
	v_or_b32_e32 v12, v12, v128
	v_mad_u64_u32 v[18:19], s[58:59], v12, s63, v[132:133]
	v_mad_i32_i24 v19, v13, s63, v19
	global_load_dwordx4 v[20:23], v[16:17], off
	global_load_dwordx4 v[48:51], v[18:19], off
	v_mad_u64_u32 v[18:19], s[58:59], v12, s65, v[134:135]
	v_mad_i32_i24 v19, v13, s65, v19
	global_load_dwordx4 v[52:55], v[18:19], off offset:16
	global_load_dwordx4 v[60:63], v[18:19], off
	s_nop 0
	global_load_dwordx4 v[12:15], v[14:15], off
	s_nop 0
	global_load_dwordx4 v[16:19], v[16:17], off offset:16
	v_mad_i64_i32 v[44:45], s[58:59], v130, s66, 0
	v_mul_hi_u32_u24_e32 v46, 0x24000, v128
	v_mul_u32_u24_e32 v47, 0x24000, v128
	v_or_b32_e32 v45, v45, v46
	v_or_b32_e32 v44, v44, v47
	v_lshl_add_u64 v[136:137], v[44:45], 0, v[40:41]
	v_mad_i64_i32 v[40:41], s[58:59], v130, s67, 0
	v_mul_hi_u32_u24_e32 v44, 0x300, v128
	v_mul_u32_u24_e32 v45, 0x300, v128
	v_or_b32_e32 v41, v41, v44
	v_or_b32_e32 v40, v40, v45
	v_lshl_add_u64 v[40:41], v[40:41], 0, v[42:43]
	v_lshl_add_u64 v[138:139], v[40:41], 0, s[34:35]
	v_mad_i64_i32 v[40:41], s[58:59], v122, s66, 0
	v_mul_hi_u32_u24_e32 v42, 0x24000, v120
	v_mul_u32_u24_e32 v43, 0x24000, v120
	v_or_b32_e32 v41, v41, v42
	v_or_b32_e32 v40, v40, v43
	v_lshl_add_u64 v[140:141], v[40:41], 0, v[36:37]
	v_mad_i64_i32 v[36:37], s[58:59], v122, s67, 0
	v_mul_hi_u32_u24_e32 v40, 0x300, v120
	v_mul_u32_u24_e32 v41, 0x300, v120
	v_or_b32_e32 v37, v37, v40
	v_or_b32_e32 v36, v36, v41
	v_lshl_add_u64 v[36:37], v[36:37], 0, v[38:39]
	v_lshl_add_u64 v[142:143], v[36:37], 0, s[34:35]
	v_mov_b32_e32 v146, 0
	s_waitcnt vmcnt(0)
	v_mov_b64_e32 v[38:39], v[30:31]
	s_mov_b32 s60, 0
	v_mov_b32_e32 v147, v146
	v_mov_b32_e32 v150, v146
	v_mov_b32_e32 v151, v146
	v_mov_b32_e32 v152, v146
	v_mov_b32_e32 v153, v146
	v_mov_b64_e32 v[42:43], v[26:27]
	v_mov_b64_e32 v[46:47], v[34:35]
	v_mov_b32_e32 v154, v146
	v_mov_b32_e32 v155, v146
	v_mov_b32_e32 v156, v146
	v_mov_b32_e32 v157, v146
	v_mov_b32_e32 v158, v146
	v_mov_b32_e32 v159, v146
	v_mov_b32_e32 v160, v146
	v_mov_b32_e32 v161, v146
	v_mov_b32_e32 v162, v146
	v_mov_b32_e32 v163, v146
	v_mov_b64_e32 v[40:41], v[24:25]
	v_mov_b64_e32 v[44:45], v[32:33]
	v_mov_b64_e32 v[36:37], v[28:29]
	v_mov_b64_e32 v[58:59], v[50:51]
	v_mov_b64_e32 v[70:71], v[54:55]
	v_mov_b64_e32 v[66:67], v[62:63]
	v_mov_b64_e32 v[56:57], v[48:49]
	v_mov_b64_e32 v[64:65], v[60:61]
	v_mov_b64_e32 v[68:69], v[52:53]
	s_branch .LBB0_549

.LBB0_549:
	v_lshl_add_u64 v[144:145], s[42:43], 0, v[140:141]
	v_add_co_u32_e32 v72, vcc, s77, v144
	v_lshl_add_u64 v[74:75], s[42:43], 0, v[142:143]
	s_nop 0
	v_addc_co_u32_e32 v73, vcc, 0, v145, vcc
	global_load_dwordx4 v[108:111], v[72:73], off
	global_load_dwordx4 v[116:119], v[74:75], off offset:-3072
	v_add_co_u32_e32 v72, vcc, s78, v144
	v_lshl_add_u64 v[148:149], s[42:43], 0, v[136:137]
	s_nop 0
	v_addc_co_u32_e32 v73, vcc, 0, v145, vcc
	global_load_dwordx4 v[100:103], v[72:73], off
	global_load_dwordx4 v[96:99], v[74:75], off offset:16
	global_load_dwordx4 v[112:115], v[74:75], off offset:-3056
	global_load_dwordx4 v[104:107], v[74:75], off
	v_add_co_u32_e32 v72, vcc, s77, v148
	v_lshl_add_u64 v[80:81], s[42:43], 0, v[138:139]
	s_nop 0
	v_addc_co_u32_e32 v73, vcc, 0, v149, vcc
	global_load_dwordx4 v[84:87], v[72:73], off
	global_load_dwordx4 v[92:95], v[80:81], off offset:-3072
	v_add_co_u32_e32 v72, vcc, s78, v148
	v_cvt_pk_bf16_f32 v164, v146, v147
	s_nop 0
	v_addc_co_u32_e32 v73, vcc, 0, v149, vcc
	global_load_dwordx4 v[76:79], v[72:73], off
	s_nop 0
	global_load_dwordx4 v[72:75], v[80:81], off offset:16
	global_load_dwordx4 v[88:91], v[80:81], off offset:-3056
	s_nop 0
	global_load_dwordx4 v[80:83], v[80:81], off
	v_add_co_u32_e32 v168, vcc, s75, v144
	v_cvt_pk_bf16_f32 v165, v150, v151
	v_cvt_pk_bf16_f32 v166, v152, v153
	v_cvt_pk_bf16_f32 v167, v154, v155
	v_addc_co_u32_e32 v169, vcc, 0, v145, vcc
	global_store_dwordx4 v[168:169], v[164:167], off sc1
	v_lshlrev_b32_e32 v168, 16, v3
	v_and_b32_e32 v169, 0xffff0000, v3
	v_lshlrev_b32_e32 v166, 16, v1
	v_and_b32_e32 v167, 0xffff0000, v1
	v_lshlrev_b32_e32 v164, 16, v0
	v_and_b32_e32 v165, 0xffff0000, v0
	v_pk_fma_f32 v[150:151], v[10:11], v[150:151], v[166:167]
	v_lshlrev_b32_e32 v166, 16, v2
	v_and_b32_e32 v167, 0xffff0000, v2
	v_pk_fma_f32 v[146:147], v[8:9], v[146:147], v[164:165]
	v_pk_fma_f32 v[152:153], v[4:5], v[152:153], v[166:167]
	v_pk_fma_f32 v[154:155], v[6:7], v[154:155], v[168:169]
	v_add_co_u32_e32 v168, vcc, s76, v144
	v_cvt_pk_bf16_f32 v164, v146, v147
	v_cvt_pk_bf16_f32 v165, v150, v151
	v_cvt_pk_bf16_f32 v166, v152, v153
	v_cvt_pk_bf16_f32 v167, v154, v155
	v_addc_co_u32_e32 v169, vcc, 0, v145, vcc
	global_store_dwordx4 v[168:169], v[164:167], off sc1
	v_add_co_u32_e32 v168, vcc, s75, v148
	s_nop 0
	v_cvt_pk_bf16_f32 v164, v156, v157
	v_cvt_pk_bf16_f32 v165, v158, v159
	v_cvt_pk_bf16_f32 v166, v160, v161
	v_cvt_pk_bf16_f32 v167, v162, v163
	v_addc_co_u32_e32 v169, vcc, 0, v149, vcc
	global_store_dwordx4 v[168:169], v[164:167], off sc1
	v_lshlrev_b32_e32 v168, 16, v15
	v_and_b32_e32 v169, 0xffff0000, v15
	v_lshlrev_b32_e32 v166, 16, v13
	v_and_b32_e32 v167, 0xffff0000, v13
	v_lshlrev_b32_e32 v164, 16, v12
	v_and_b32_e32 v165, 0xffff0000, v12
	v_pk_fma_f32 v[158:159], v[22:23], v[158:159], v[166:167]
	v_lshlrev_b32_e32 v166, 16, v14
	v_and_b32_e32 v167, 0xffff0000, v14
	v_pk_fma_f32 v[162:163], v[18:19], v[162:163], v[168:169]
	v_add_co_u32_e32 v168, vcc, 0x14894000, v148
	s_cmp_gt_u32 s60, 59
	v_pk_fma_f32 v[156:157], v[20:21], v[156:157], v[164:165]
	v_pk_fma_f32 v[160:161], v[16:17], v[160:161], v[166:167]
	v_addc_co_u32_e32 v169, vcc, 0, v149, vcc
	s_cselect_b64 s[58:59], -1, 0
	v_cvt_pk_bf16_f32 v164, v156, v157
	v_cvt_pk_bf16_f32 v165, v158, v159
	v_cvt_pk_bf16_f32 v166, v160, v161
	v_cvt_pk_bf16_f32 v167, v162, v163
	s_and_b64 vcc, exec, s[58:59]
	global_store_dwordx4 v[168:169], v[164:167], off sc1
	s_cbranch_vccnz .LBB0_548
	v_add_u32_e32 v10, s60, v122
	v_add_u32_e32 v0, 4, v10
	v_add_u32_e32 v10, 5, v10
	v_ashrrev_i32_e32 v1, 31, v0
	v_ashrrev_i32_e32 v11, 31, v10
	v_lshlrev_b64 v[0:1], 2, v[0:1]
	v_lshlrev_b64 v[12:13], 2, v[10:11]
	v_or_b32_e32 v0, v0, v120
	v_or_b32_e32 v12, v12, v120
	v_mad_u64_u32 v[2:3], s[80:81], v0, s63, v[124:125]
	v_mad_u64_u32 v[8:9], s[80:81], v0, s65, v[126:127]
	v_mad_u64_u32 v[14:15], s[80:81], v12, s63, v[124:125]
	v_mad_i32_i24 v3, v1, s63, v3
	v_mad_i32_i24 v9, v1, s65, v9
	v_mad_i32_i24 v15, v13, s63, v15
	v_add_u32_e32 v22, s60, v130
	global_load_dwordx4 v[0:3], v[2:3], off
	s_nop 0
	global_load_dwordx4 v[4:7], v[8:9], off offset:16
	s_nop 0
	global_load_dwordx4 v[8:11], v[8:9], off
	s_nop 0
	global_load_dwordx4 v[36:39], v[14:15], off
	v_mad_u64_u32 v[14:15], s[80:81], v12, s65, v[126:127]
	v_add_u32_e32 v12, 4, v22
	v_add_u32_e32 v22, 5, v22
	v_mad_i32_i24 v15, v13, s65, v15
	v_ashrrev_i32_e32 v13, 31, v12
	v_ashrrev_i32_e32 v23, 31, v22
	v_lshlrev_b64 v[12:13], 2, v[12:13]
	v_lshlrev_b64 v[64:65], 2, v[22:23]
	v_or_b32_e32 v12, v12, v128
	v_or_b32_e32 v64, v64, v128
	global_load_dwordx4 v[40:43], v[14:15], off offset:16
	global_load_dwordx4 v[44:47], v[14:15], off
	v_mad_u64_u32 v[14:15], s[80:81], v12, s63, v[132:133]
	v_mad_u64_u32 v[20:21], s[80:81], v12, s65, v[134:135]
	v_mad_u64_u32 v[56:57], s[80:81], v64, s63, v[132:133]
	v_mad_u64_u32 v[66:67], s[80:81], v64, s65, v[134:135]
	v_mad_i32_i24 v15, v13, s63, v15
	v_mad_i32_i24 v21, v13, s65, v21
	v_mad_i32_i24 v57, v65, s63, v57
	v_mad_i32_i24 v67, v65, s65, v67
	global_load_dwordx4 v[12:15], v[14:15], off
	s_nop 0
	global_load_dwordx4 v[16:19], v[20:21], off offset:16
	s_nop 0
	global_load_dwordx4 v[20:23], v[20:21], off
	s_nop 0
	global_load_dwordx4 v[56:59], v[56:57], off
	s_nop 0
	global_load_dwordx4 v[68:71], v[66:67], off offset:16
	s_nop 0
	global_load_dwordx4 v[64:67], v[66:67], off
	s_branch .LBB0_548

.LBB0_605:
	s_cmp_lt_i32 s44, 5
	s_cselect_b64 s[6:7], -1, 0
	s_and_b64 s[52:53], s[6:7], s[8:9]
	s_xor_b64 s[6:7], s[52:53], -1
	s_cmpk_gt_i32 s2, 0x3ff
	s_cselect_b64 s[8:9], -1, 0
	s_or_b64 s[6:7], s[8:9], s[6:7]
	s_and_b64 vcc, exec, s[6:7]
	s_cbranch_vccnz .LBB0_628
	s_ashr_i32 s6, s2, 8
	s_ashr_i32 s7, s6, 31
	s_lshl_b32 s3, s2, 4
	s_lshl_b64 s[6:7], s[6:7], 12
	s_and_b32 s8, s3, 0xfc0
	s_or_b32 s6, s6, s8
	s_add_u32 s65, s42, 0x14804000
	s_addc_u32 s67, s43, 0
	s_mul_i32 s8, s2, 0x24000
	s_mul_hi_i32 s9, s2, 0x24000
	s_add_u32 s8, s65, s8
	v_readfirstlane_b32 s10, v213
	s_addc_u32 s9, s67, s9
	s_lshr_b32 s10, s10, 7
	s_mulk_i32 s10, 0x900
	v_or_b32_e32 v0, s10, v228
	v_ashrrev_i32_e32 v1, 31, v0
	v_or_b32_e32 v4, 64, v0
	v_lshl_add_u64 v[2:3], v[0:1], 4, s[8:9]
	v_ashrrev_i32_e32 v5, 31, v4
	v_lshl_add_u64 v[4:5], v[4:5], 4, s[8:9]
	global_load_dwordx4 v[48:51], v[2:3], off
	global_load_dwordx4 v[52:55], v[4:5], off
	v_or_b32_e32 v2, 0x80, v0
	v_or_b32_e32 v0, 0xc0, v0
	v_ashrrev_i32_e32 v3, 31, v2
	v_ashrrev_i32_e32 v1, 31, v0
	v_lshl_add_u64 v[2:3], v[2:3], 4, s[8:9]
	v_lshl_add_u64 v[0:1], v[0:1], 4, s[8:9]
	s_add_i32 s11, s10, 0x100
	global_load_dwordx4 v[56:59], v[2:3], off
	global_load_dwordx4 v[60:63], v[0:1], off
	v_or_b32_e32 v0, s11, v228
	s_add_i32 s11, s10, 0x140
	v_ashrrev_i32_e32 v1, 31, v0
	v_or_b32_e32 v2, s11, v228
	v_lshl_add_u64 v[0:1], v[0:1], 4, s[8:9]
	v_ashrrev_i32_e32 v3, 31, v2
	s_add_i32 s11, s10, 0x180
	v_lshl_add_u64 v[2:3], v[2:3], 4, s[8:9]
	global_load_dwordx4 v[64:67], v[0:1], off
	global_load_dwordx4 v[68:71], v[2:3], off
	v_or_b32_e32 v0, s11, v228
	s_add_i32 s11, s10, 0x1c0
	v_ashrrev_i32_e32 v1, 31, v0
	v_or_b32_e32 v2, s11, v228
	v_lshl_add_u64 v[0:1], v[0:1], 4, s[8:9]
	v_ashrrev_i32_e32 v3, 31, v2
	s_add_i32 s11, s10, 0x200
	v_lshl_add_u64 v[2:3], v[2:3], 4, s[8:9]
	global_load_dwordx4 v[72:75], v[0:1], off
	global_load_dwordx4 v[76:79], v[2:3], off
	v_or_b32_e32 v0, s11, v228
	s_add_i32 s11, s10, 0x240
	v_ashrrev_i32_e32 v1, 31, v0
	v_or_b32_e32 v2, s11, v228
	v_lshl_add_u64 v[0:1], v[0:1], 4, s[8:9]
	v_ashrrev_i32_e32 v3, 31, v2
	s_add_i32 s11, s10, 0x280
	v_lshl_add_u64 v[2:3], v[2:3], 4, s[8:9]
	global_load_dwordx4 v[84:87], v[0:1], off
	global_load_dwordx4 v[92:95], v[2:3], off
	v_or_b32_e32 v0, s11, v228
	s_addk_i32 s10, 0x2c0
	v_ashrrev_i32_e32 v1, 31, v0
	v_or_b32_e32 v2, s10, v228
	v_lshl_add_u64 v[0:1], v[0:1], 4, s[8:9]
	v_ashrrev_i32_e32 v3, 31, v2
	s_and_b32 s10, s2, 3
	v_lshl_add_u64 v[2:3], v[2:3], 4, s[8:9]
	global_load_dwordx4 v[96:99], v[0:1], off
	global_load_dwordx4 v[100:103], v[2:3], off
	s_add_u32 s54, s42, 0x9004000
	v_mul_u32_u24_e32 v0, 0xaab, v213
	v_mov_b32_e32 v1, 24
	s_addc_u32 s55, s43, 0
	v_mul_lo_u16_sdwa v1, v0, v1 dst_sel:DWORD dst_unused:UNUSED_PAD src0_sel:WORD_1 src1_sel:DWORD
	v_sub_u16_e32 v4, v213, v1
	v_or_b32_sdwa v2, s6, v0 dst_sel:DWORD dst_unused:UNUSED_PAD src0_sel:DWORD src1_sel:WORD_1
	s_movk_i32 s70, 0x2200
	v_mov_b64_e32 v[0:1], s[54:55]
	v_mad_u64_u32 v[2:3], s[8:9], v2, s70, v[0:1]
	v_mov_b32_e32 v5, 0x2200
	v_mad_i32_i24 v3, s7, v5, v3
	s_mul_i32 s56, s10, 0x180
	s_mov_b32 s57, 0
	v_lshlrev_b16_e32 v4, 3, v4
	v_lshl_add_u64 v[2:3], v[2:3], 0, s[56:57]
	v_lshlrev_b32_e32 v216, 1, v4
	v_mov_b32_e32 v217, 0
	v_lshl_add_u64 v[2:3], v[2:3], 0, v[216:217]
	global_load_dwordx4 v[80:83], v[2:3], off offset:1536
	global_load_dwordx4 v[88:91], v[2:3], off
	v_add_u16_e32 v2, 0x200, v213
	v_mul_u32_u24_e32 v3, 0xaab, v2
	v_lshrrev_b32_e32 v216, 16, v3
	v_mul_lo_u16_e32 v3, 24, v216
	v_sub_u16_e32 v6, v2, v3
	v_lshl_add_u64 v[2:3], s[6:7], 0, v[216:217]
	v_mad_u64_u32 v[4:5], s[8:9], v2, s70, v[0:1]
	v_mad_i32_i24 v5, v3, s70, v5
	v_lshl_add_u64 v[2:3], v[4:5], 0, s[56:57]
	v_lshlrev_b16_e32 v4, 3, v6
	v_lshlrev_b32_e32 v216, 1, v4
	v_lshl_add_u64 v[2:3], v[2:3], 0, v[216:217]
	s_movk_i32 s11, 0xaab
	global_load_dwordx4 v[104:107], v[2:3], off offset:1536
	global_load_dwordx4 v[108:111], v[2:3], off
	v_or_b32_e32 v2, 0x400, v213
	v_mul_u32_u24_sdwa v3, v2, s11 dst_sel:DWORD dst_unused:UNUSED_PAD src0_sel:WORD_0 src1_sel:DWORD
	v_lshrrev_b32_e32 v216, 16, v3
	v_mul_lo_u16_e32 v3, 24, v216
	v_sub_u16_e32 v4, v2, v3
	v_lshl_add_u64 v[2:3], s[6:7], 0, v[216:217]
	v_mad_u64_u32 v[0:1], s[6:7], v2, s70, v[0:1]
	v_mad_i32_i24 v1, v3, s70, v1
	v_lshlrev_b16_e32 v2, 3, v4
	v_lshl_add_u64 v[0:1], v[0:1], 0, s[56:57]
	v_lshlrev_b32_e32 v216, 1, v2
	v_lshl_add_u64 v[0:1], v[0:1], 0, v[216:217]
	global_load_dwordx4 v[112:115], v[0:1], off offset:1536
	global_load_dwordx4 v[116:119], v[0:1], off
	s_add_u32 s58, s42, 0x11804000
	s_addc_u32 s59, s43, 0
	s_add_u32 s71, s42, 0x5004000
	v_mbcnt_lo_u32_b32 v0, -1, 0
	s_addc_u32 s72, s43, 0
	s_lshl_b32 s73, s46, 4
	s_mov_b32 s74, 0x2aaaaaab
	s_movk_i32 s75, 0x190
	s_movk_i32 s76, 0x310
	s_mov_b64 s[60:61], 0x100000
	s_mov_b32 s77, 0x100000
	s_mov_b64 s[62:63], 0x200000
	s_mov_b32 s78, 0x200000
	v_mbcnt_hi_u32_b32 v229, -1, v0
	s_movk_i32 s79, 0x30c
	s_mov_b32 s80, 0x9004000
	s_mov_b32 s64, 0x3b2aaaab
	s_mov_b32 s66, 0x358637bd
	s_mov_b32 s81, 0x800000
	s_mov_b32 s82, s2
	s_branch .LBB0_608
.LBB0_607:
	s_or_b64 exec, exec, s[6:7]
	s_waitcnt lgkmcnt(0)
	v_ashrrev_i32_e32 v0, 3, v237
	v_add_u32_e32 v0, v0, v238
	v_mul_lo_u32 v1, v0, 48
	v_sub_u32_e32 v12, v230, v1
	v_ashrrev_i32_e32 v1, 31, v0
	v_lshl_add_u64 v[10:11], s[12:13], 0, v[0:1]
	v_mov_b64_e32 v[8:9], s[42:43]
	v_mad_u64_u32 v[4:5], s[6:7], v10, s70, v[8:9]
	v_mov_b32_e32 v6, v5
	v_lshlrev_b32_e32 v2, 3, v12
	v_mad_u64_u32 v[6:7], s[6:7], v11, s70, v[6:7]
	s_mul_i32 s56, s16, 0x300
	v_mov_b32_e32 v5, v6
	v_ashrrev_i32_e32 v3, 31, v2
	v_lshl_add_u64 v[4:5], v[4:5], 0, s[56:57]
	v_lshlrev_b64 v[16:17], 1, v[2:3]
	v_lshl_add_u64 v[4:5], v[4:5], 0, v[16:17]
	v_add_co_u32_e32 v4, vcc, s80, v4
	s_nop 1
	v_addc_co_u32_e32 v5, vcc, 0, v5, vcc
	s_barrier
	global_load_dwordx4 v[22:25], v[4:5], off offset:3072
	v_lshl_add_u32 v1, v0, 2, 0
	v_mul_lo_u32 v0, v0, s79
	v_lshlrev_b32_e32 v4, 4, v12
	v_add3_u32 v0, v1, v0, v4
	s_load_dwordx2 s[18:19], s[0:1], 0x38
	ds_read_b128 v[26:29], v0 offset:63488
	ds_read2st64_b32 v[18:19], v1 offset0:16 offset1:17
	ds_read2st64_b32 v[14:15], v1 offset0:18 offset1:19
	s_add_u32 s16, s71, s56
	s_addc_u32 s17, s72, 0
	s_waitcnt lgkmcnt(0)
	v_lshlrev_b32_e32 v12, 16, v26
	v_and_b32_e32 v13, 0xffff0000, v26
	v_lshlrev_b32_e32 v20, 16, v27
	v_and_b32_e32 v21, 0xffff0000, v27
	v_lshl_add_u64 v[4:5], v[2:3], 2, s[18:19]
	global_load_dwordx4 v[0:3], v[4:5], off offset:16
	s_nop 0
	global_load_dwordx4 v[4:7], v[4:5], off
	v_lshlrev_b64 v[10:11], 12, v[10:11]
	v_lshl_add_u64 v[10:11], s[16:17], 0, v[10:11]
	v_lshl_add_u64 v[16:17], v[10:11], 0, v[16:17]
	s_add_i32 s3, s3, s73
	s_waitcnt vmcnt(2)
	v_lshlrev_b32_e32 v30, 16, v22
	v_and_b32_e32 v31, 0xffff0000, v22
	v_lshlrev_b32_e32 v32, 16, v23
	v_and_b32_e32 v33, 0xffff0000, v23
	v_mul_f32_e32 v22, 0xbfb8aa3b, v30
	v_mul_f32_e32 v23, 0xbfb8aa3b, v31
	v_exp_f32_e32 v22, v22
	v_exp_f32_e32 v23, v23
	v_mul_f32_e32 v26, 0xbfb8aa3b, v32
	v_mul_f32_e32 v27, 0xbfb8aa3b, v33
	v_exp_f32_e32 v26, v26
	v_exp_f32_e32 v27, v27
	v_pk_add_f32 v[22:23], v[22:23], 1.0 op_sel_hi:[1,0]
	v_lshlrev_b32_e32 v34, 16, v24
	v_div_scale_f32 v36, s[6:7], v23, v23, v31
	v_pk_add_f32 v[26:27], v[26:27], 1.0 op_sel_hi:[1,0]
	v_div_scale_f32 v38, s[6:7], v22, v22, v30
	v_rcp_f32_e32 v44, v36
	v_div_scale_f32 v40, s[8:9], v27, v27, v33
	v_rcp_f32_e32 v45, v38
	v_rcp_f32_e32 v46, v40
	v_fma_f32 v120, -v36, v44, 1.0
	v_div_scale_f32 v37, vcc, v31, v23, v31
	v_fma_f32 v121, -v38, v45, 1.0
	v_fmac_f32_e32 v44, v120, v44
	v_div_scale_f32 v39, s[6:7], v30, v22, v30
	v_fma_f32 v122, -v40, v46, 1.0
	v_fmac_f32_e32 v45, v121, v45
	v_mul_f32_e32 v120, v37, v44
	v_div_scale_f32 v41, s[8:9], v33, v27, v33
	v_fmac_f32_e32 v46, v122, v46
	v_mul_f32_e32 v121, v39, v45
	v_fma_f32 v124, -v36, v120, v37
	v_mul_f32_e32 v122, v41, v46
	v_fma_f32 v125, -v38, v121, v39
	v_fmac_f32_e32 v120, v124, v44
	v_fma_f32 v126, -v40, v122, v41
	v_fmac_f32_e32 v121, v125, v45
	v_fmac_f32_e32 v122, v126, v46
	s_mov_b64 vcc, s[6:7]
	v_and_b32_e32 v24, 0xffff0000, v24
	v_div_scale_f32 v42, s[10:11], v26, v26, v32
	v_rcp_f32_e32 v36, v23
	s_nop 0
	v_mul_f32_e32 v23, v31, v36
	s_mov_b64 vcc, s[8:9]
	v_mul_f32_e32 v35, 0xbfb8aa3b, v34
	v_rcp_f32_e32 v47, v42
	v_rcp_f32_e32 v31, v22
	s_nop 0
	v_mul_f32_e32 v22, v30, v31
	v_mul_f32_e32 v31, 0xbfb8aa3b, v24
	v_rcp_f32_e32 v30, v27
	s_nop 0
	v_mul_f32_e32 v27, v33, v30
	v_exp_f32_e32 v30, v35
	v_exp_f32_e32 v31, v31
	v_fma_f32 v123, -v42, v47, 1.0
	v_div_scale_f32 v43, s[10:11], v32, v26, v32
	v_fmac_f32_e32 v47, v123, v47
	v_pk_add_f32 v[30:31], v[30:31], 1.0 op_sel_hi:[1,0]
	v_mul_f32_e32 v123, v43, v47
	v_fma_f32 v127, -v42, v123, v43
	v_fmac_f32_e32 v123, v127, v47
	s_mov_b64 vcc, s[10:11]
	v_rcp_f32_e32 v33, v26
	s_nop 0
	v_mul_f32_e32 v26, v32, v33
	v_lshlrev_b32_e32 v32, 16, v28
	v_and_b32_e32 v33, 0xffff0000, v28
	v_rcp_f32_e32 v28, v31
	s_nop 0
	v_mul_f32_e32 v31, v24, v28
	v_lshlrev_b32_e32 v37, 16, v25
	v_and_b32_e32 v39, 0xffff0000, v25
	v_mul_f32_e32 v24, 0xbfb8aa3b, v37
	v_mul_f32_e32 v25, 0xbfb8aa3b, v39
	v_exp_f32_e32 v24, v24
	v_exp_f32_e32 v25, v25
	v_rcp_f32_e32 v28, v30
	s_nop 0
	v_mul_f32_e32 v30, v34, v28
	v_pk_add_f32 v[24:25], v[24:25], 1.0 op_sel_hi:[1,0]
	v_lshlrev_b32_e32 v28, 16, v29
	v_and_b32_e32 v29, 0xffff0000, v29
	v_rcp_f32_e32 v34, v25
	s_nop 0
	v_mul_f32_e32 v25, v39, v34
	v_mov_b32_e32 v39, v18
	v_div_scale_f32 v34, vcc, v37, v24, v37
	v_rcp_f32_e32 v34, v24
	s_nop 0
	v_mul_f32_e32 v24, v37, v34
	v_ashrrev_i32_e32 v34, 3, v235
	v_add_u32_e32 v34, v34, v236
	v_lshl_add_u32 v40, v34, 2, 0
	ds_read2st64_b32 v[36:37], v40 offset0:16 offset1:17
	ds_read2st64_b32 v[10:11], v40 offset0:18 offset1:19
	v_mul_lo_u32 v35, v34, 48
	s_waitcnt lgkmcnt(1)
	v_mov_b32_e32 v38, v36
	v_mov_b32_e32 v18, v37
	v_pk_add_f32 v[18:19], v[38:39], v[18:19]
	s_waitcnt lgkmcnt(0)
	v_mov_b32_e32 v36, v10
	v_mov_b32_e32 v37, v14
	v_pk_add_f32 v[18:19], v[18:19], v[36:37]
	v_mov_b32_e32 v14, v11
	v_pk_add_f32 v[14:15], v[18:19], v[14:15]
	v_mov_b64_e32 v[10:11], s[66:67]
	v_pk_fma_f32 v[36:37], v[14:15], s[64:65], v[10:11] op_sel_hi:[1,0,0]
	s_nop 0
	v_mul_f32_e32 v14, 0x4b800000, v37
	v_cmp_gt_f32_e32 vcc, s81, v37
	s_nop 1
	v_cndmask_b32_e32 v14, v37, v14, vcc
	v_rsq_f32_e32 v15, v14
	v_sub_u32_e32 v37, v234, v35
	v_ashrrev_i32_e32 v35, 31, v34
	v_lshlrev_b32_e32 v14, 3, v37
	v_mul_f32_e32 v18, 0x45800000, v15
	v_cndmask_b32_e32 v18, v15, v18, vcc
	v_pk_mul_f32 v[12:13], v[18:19], v[12:13] op_sel_hi:[0,1]
	s_waitcnt vmcnt(0)
	v_pk_mul_f32 v[4:5], v[4:5], v[12:13]
	v_pk_mul_f32 v[12:13], v[18:19], v[20:21] op_sel_hi:[0,1]
	v_pk_mul_f32 v[6:7], v[6:7], v[12:13]
	v_pk_mul_f32 v[4:5], v[22:23], v[4:5]
	v_pk_mul_f32 v[6:7], v[26:27], v[6:7]
	v_cvt_pk_bf16_f32 v4, v4, v5
	v_cvt_pk_bf16_f32 v5, v6, v7
	v_pk_mul_f32 v[6:7], v[18:19], v[32:33] op_sel_hi:[0,1]
	v_pk_mul_f32 v[0:1], v[0:1], v[6:7]
	v_ashrrev_i32_e32 v15, 31, v14
	v_pk_mul_f32 v[0:1], v[30:31], v[0:1]
	v_mul_f32_e32 v20, 0x4b800000, v36
	v_cvt_pk_bf16_f32 v6, v0, v1
	v_pk_mul_f32 v[0:1], v[18:19], v[28:29] op_sel_hi:[0,1]
	v_pk_mul_f32 v[0:1], v[2:3], v[0:1]
	v_lshlrev_b32_e32 v21, 4, v37
	v_pk_mul_f32 v[0:1], v[24:25], v[0:1]
	s_nop 0
	v_cvt_pk_bf16_f32 v7, v0, v1
	v_lshl_add_u64 v[0:1], s[12:13], 0, v[34:35]
	v_mad_u64_u32 v[2:3], s[6:7], v0, s70, v[8:9]
	global_store_dwordx4 v[16:17], v[4:7], off sc1
	v_lshl_add_u64 v[16:17], v[14:15], 2, s[18:19]
	s_nop 0
	v_mov_b32_e32 v4, v3
	v_mad_u64_u32 v[4:5], s[6:7], v1, s70, v[4:5]
	v_mov_b32_e32 v3, v4
	v_lshl_add_u64 v[2:3], v[2:3], 0, s[56:57]
	v_lshlrev_b64 v[6:7], 1, v[14:15]
	v_lshl_add_u64 v[2:3], v[2:3], 0, v[6:7]
	v_add_co_u32_e32 v2, vcc, s80, v2
	v_lshlrev_b64 v[0:1], 12, v[0:1]
	s_nop 0
	v_addc_co_u32_e32 v3, vcc, 0, v3, vcc
	global_load_dwordx4 v[2:5], v[2:3], off offset:3072
	s_nop 0
	global_load_dwordx4 v[12:15], v[16:17], off
	s_nop 0
	global_load_dwordx4 v[16:19], v[16:17], off offset:16
	v_cmp_gt_f32_e32 vcc, s81, v36
	v_lshl_add_u64 v[0:1], s[16:17], 0, v[0:1]
	v_lshl_add_u64 v[0:1], v[0:1], 0, v[6:7]
	v_cndmask_b32_e32 v20, v36, v20, vcc
	v_rsq_f32_e32 v26, v20
	v_mul_lo_u32 v20, v34, s79
	v_add3_u32 v20, v40, v20, v21
	ds_read_b128 v[20:23], v20 offset:63488
	v_mul_f32_e32 v28, 0x45800000, v26
	v_cndmask_b32_e32 v26, v26, v28, vcc
	s_waitcnt lgkmcnt(0)
	v_lshlrev_b32_e32 v28, 16, v20
	v_and_b32_e32 v29, 0xffff0000, v20
	s_waitcnt vmcnt(2)
	v_lshlrev_b32_e32 v27, 16, v2
	v_and_b32_e32 v2, 0xffff0000, v2
	v_mul_f32_e32 v24, 0xbfb8aa3b, v27
	v_mul_f32_e32 v25, 0xbfb8aa3b, v2
	v_exp_f32_e32 v24, v24
	v_exp_f32_e32 v25, v25
	v_pk_mul_f32 v[28:29], v[26:27], v[28:29] op_sel_hi:[0,1]
	s_waitcnt vmcnt(1)
	v_pk_mul_f32 v[12:13], v[12:13], v[28:29]
	v_pk_add_f32 v[24:25], v[24:25], 1.0 op_sel_hi:[1,0]
	s_nop 0
	s_nop 0
	v_rcp_f32_e32 v20, v25
	s_nop 0
	v_mul_f32_e32 v25, v2, v20
	v_lshlrev_b32_e32 v20, 16, v3
	v_rcp_f32_e32 v2, v24
	s_nop 0
	v_mul_f32_e32 v24, v27, v2
	v_and_b32_e32 v27, 0xffff0000, v3
	v_mul_f32_e32 v2, 0xbfb8aa3b, v20
	v_exp_f32_e32 v28, v2
	v_mul_f32_e32 v2, 0xbfb8aa3b, v27
	v_exp_f32_e32 v29, v2
	v_pk_mul_f32 v[2:3], v[24:25], v[12:13]
	v_lshlrev_b32_e32 v12, 16, v21
	v_cvt_pk_bf16_f32 v2, v2, v3
	v_pk_add_f32 v[24:25], v[28:29], 1.0 op_sel_hi:[1,0]
	v_and_b32_e32 v13, 0xffff0000, v21
	v_pk_mul_f32 v[12:13], v[26:27], v[12:13] op_sel_hi:[0,1]
	v_pk_mul_f32 v[12:13], v[14:15], v[12:13]
	v_div_scale_f32 v14, s[6:7], v24, v24, v20
	v_rcp_f32_e32 v21, v14
	v_rcp_f32_e32 v3, v25
	s_nop 0
	v_mul_f32_e32 v15, v27, v3
	v_fma_f32 v3, -v14, v21, 1.0
	v_fmac_f32_e32 v21, v3, v21
	v_div_scale_f32 v3, vcc, v20, v24, v20
	v_mul_f32_e32 v25, v3, v21
	v_fma_f32 v27, -v14, v25, v3
	v_rcp_f32_e32 v3, v24
	s_nop 0
	v_mul_f32_e32 v14, v20, v3
	v_lshlrev_b32_e32 v24, 16, v4
	v_and_b32_e32 v4, 0xffff0000, v4
	v_mul_f32_e32 v3, 0xbfb8aa3b, v24
	v_exp_f32_e32 v20, v3
	v_mul_f32_e32 v3, 0xbfb8aa3b, v4
	v_exp_f32_e32 v21, v3
	v_pk_mul_f32 v[12:13], v[14:15], v[12:13]
	v_pk_add_f32 v[14:15], v[20:21], 1.0 op_sel_hi:[1,0]
	s_nop 0
	v_cvt_pk_bf16_f32 v3, v12, v13
	v_lshlrev_b32_e32 v12, 16, v22
	v_and_b32_e32 v13, 0xffff0000, v22
	v_pk_mul_f32 v[12:13], v[26:27], v[12:13] op_sel_hi:[0,1]
	s_waitcnt vmcnt(0)
	v_pk_mul_f32 v[12:13], v[16:17], v[12:13]
	v_rcp_f32_e32 v16, v15
	s_nop 0
	v_mul_f32_e32 v15, v4, v16
	v_and_b32_e32 v21, 0xffff0000, v5
	v_lshlrev_b32_e32 v20, 16, v5
	v_rcp_f32_e32 v4, v14
	s_nop 0
	v_mul_f32_e32 v14, v24, v4
	v_mul_f32_e32 v4, 0xbfb8aa3b, v20
	v_exp_f32_e32 v16, v4
	v_mul_f32_e32 v4, 0xbfb8aa3b, v21
	v_exp_f32_e32 v17, v4
	v_pk_mul_f32 v[4:5], v[14:15], v[12:13]
	v_lshlrev_b32_e32 v12, 16, v23
	v_cvt_pk_bf16_f32 v4, v4, v5
	v_pk_add_f32 v[14:15], v[16:17], 1.0 op_sel_hi:[1,0]
	v_and_b32_e32 v13, 0xffff0000, v23
	v_pk_mul_f32 v[12:13], v[26:27], v[12:13] op_sel_hi:[0,1]
	v_pk_mul_f32 v[12:13], v[18:19], v[12:13]
	v_rcp_f32_e32 v5, v15
	s_nop 0
	v_mul_f32_e32 v15, v21, v5
	v_rcp_f32_e32 v5, v14
	s_nop 0
	v_mul_f32_e32 v14, v20, v5
	v_pk_mul_f32 v[12:13], v[14:15], v[12:13]
	s_nop 0
	v_cvt_pk_bf16_f32 v5, v12, v13
	global_store_dwordx4 v[0:1], v[2:5], off sc1
	v_ashrrev_i32_e32 v0, 3, v232
	v_add_u32_e32 v0, v0, v233
	v_mul_lo_u32 v1, v0, 48
	v_sub_u32_e32 v12, v231, v1
	v_ashrrev_i32_e32 v1, 31, v0
	v_lshl_add_u64 v[20:21], s[12:13], 0, v[0:1]
	v_mad_u64_u32 v[4:5], s[6:7], v20, s70, v[8:9]
	v_mov_b32_e32 v6, v5
	v_lshlrev_b32_e32 v2, 3, v12
	v_mad_u64_u32 v[6:7], s[6:7], v21, s70, v[6:7]
	v_mov_b32_e32 v5, v6
	v_ashrrev_i32_e32 v3, 31, v2
	v_lshl_add_u64 v[4:5], v[4:5], 0, s[56:57]
	v_lshlrev_b64 v[22:23], 1, v[2:3]
	v_lshl_add_u64 v[4:5], v[4:5], 0, v[22:23]
	v_add_co_u32_e32 v4, vcc, s80, v4
	v_lshl_add_u32 v13, v0, 2, 0
	s_nop 0
	v_addc_co_u32_e32 v5, vcc, 0, v5, vcc
	global_load_dwordx4 v[4:7], v[4:5], off offset:3072
	v_mul_lo_u32 v14, v0, s79
	v_lshlrev_b32_e32 v12, 4, v12
	v_add3_u32 v12, v13, v14, v12
	ds_read2st64_b32 v[24:25], v13 offset0:16 offset1:17
	ds_read2st64_b32 v[26:27], v13 offset0:18 offset1:19
	ds_read_b128 v[12:15], v12 offset:63488
	v_lshl_add_u64 v[16:17], v[2:3], 2, s[18:19]
	s_waitcnt lgkmcnt(0)
	v_lshlrev_b32_e32 v30, 16, v12
	v_and_b32_e32 v31, 0xffff0000, v12
	s_waitcnt vmcnt(0)
	v_lshlrev_b32_e32 v32, 16, v4
	v_and_b32_e32 v4, 0xffff0000, v4
	v_mul_f32_e32 v0, 0xbfb8aa3b, v32
	v_mul_f32_e32 v1, 0xbfb8aa3b, v4
	v_exp_f32_e32 v0, v0
	v_exp_f32_e32 v1, v1
	v_lshlrev_b32_e32 v37, 16, v5
	v_lshlrev_b32_e32 v40, 16, v6
	v_and_b32_e32 v6, 0xffff0000, v6
	v_pk_add_f32 v[28:29], v[0:1], 1.0 op_sel_hi:[1,0]
	global_load_dwordx4 v[0:3], v[16:17], off offset:16
	s_nop 0
	global_load_dwordx4 v[16:19], v[16:17], off
	v_lshlrev_b32_e32 v41, 16, v7
	v_and_b32_e32 v7, 0xffff0000, v7
	v_rcp_f32_e32 v12, v29
	s_nop 0
	v_mul_f32_e32 v29, v4, v12
	v_and_b32_e32 v35, 0xffff0000, v5
	v_mul_f32_e32 v4, 0xbfb8aa3b, v37
	v_mul_f32_e32 v5, 0xbfb8aa3b, v35
	v_exp_f32_e32 v4, v4
	v_exp_f32_e32 v5, v5
	v_rcp_f32_e32 v12, v28
	s_nop 0
	v_mul_f32_e32 v28, v32, v12
	v_pk_add_f32 v[4:5], v[4:5], 1.0 op_sel_hi:[1,0]
	v_lshlrev_b32_e32 v12, 16, v13
	v_and_b32_e32 v13, 0xffff0000, v13
	v_rcp_f32_e32 v32, v5
	s_nop 0
	v_mul_f32_e32 v33, v35, v32
	v_mul_f32_e32 v34, 0xbfb8aa3b, v40
	v_mul_f32_e32 v35, 0xbfb8aa3b, v6
	v_exp_f32_e32 v34, v34
	v_exp_f32_e32 v35, v35
	v_rcp_f32_e32 v5, v4
	s_nop 0
	v_mul_f32_e32 v32, v37, v5
	v_pk_add_f32 v[34:35], v[34:35], 1.0 op_sel_hi:[1,0]
	v_lshlrev_b32_e32 v36, 16, v14
	v_and_b32_e32 v37, 0xffff0000, v14
	v_rcp_f32_e32 v4, v35
	s_nop 0
	v_mul_f32_e32 v35, v6, v4
	v_mul_f32_e32 v4, 0xbfb8aa3b, v41
	v_mul_f32_e32 v5, 0xbfb8aa3b, v7
	v_exp_f32_e32 v4, v4
	v_exp_f32_e32 v5, v5
	v_rcp_f32_e32 v6, v34
	s_nop 0
	v_mul_f32_e32 v34, v40, v6
	v_pk_add_f32 v[4:5], v[4:5], 1.0 op_sel_hi:[1,0]
	v_lshlrev_b32_e32 v14, 16, v15
	v_and_b32_e32 v15, 0xffff0000, v15
	v_rcp_f32_e32 v6, v5
	s_nop 0
	v_mul_f32_e32 v39, v7, v6
	v_div_scale_f32 v5, vcc, v41, v4, v41
	v_rcp_f32_e32 v5, v4
	s_nop 0
	v_mul_f32_e32 v38, v41, v5
	v_lshlrev_b64 v[4:5], 12, v[20:21]
	v_add_u32_e32 v21, 0x600, v230
	v_mul_hi_i32 v6, v21, s74
	v_lshrrev_b32_e32 v7, 31, v6
	v_ashrrev_i32_e32 v6, 3, v6
	v_add_u32_e32 v20, v6, v7
	v_lshl_add_u32 v42, v20, 2, 0
	ds_read2st64_b32 v[6:7], v42 offset0:16 offset1:17
	v_lshl_add_u64 v[4:5], s[16:17], 0, v[4:5]
	v_lshl_add_u64 v[22:23], v[4:5], 0, v[22:23]
	ds_read2st64_b32 v[4:5], v42 offset0:18 offset1:19
	v_mov_b32_e32 v41, v24
	s_waitcnt lgkmcnt(1)
	v_mov_b32_e32 v40, v6
	v_mov_b32_e32 v24, v7
	v_pk_add_f32 v[6:7], v[40:41], v[24:25]
	s_waitcnt lgkmcnt(0)
	v_mov_b32_e32 v24, v4
	v_mov_b32_e32 v25, v26
	v_pk_add_f32 v[6:7], v[6:7], v[24:25]
	v_mov_b32_e32 v26, v5
	v_pk_add_f32 v[4:5], v[6:7], v[26:27]
	v_mul_lo_u32 v43, v20, 48
	v_pk_fma_f32 v[24:25], v[4:5], s[64:65], v[10:11] op_sel_hi:[1,0,0]
	s_nop 0
	v_mul_f32_e32 v4, 0x4b800000, v25
	v_cmp_gt_f32_e32 vcc, s81, v25
	s_nop 1
	v_cndmask_b32_e32 v4, v25, v4, vcc
	v_rsq_f32_e32 v4, v4
	v_sub_u32_e32 v25, v21, v43
	v_ashrrev_i32_e32 v21, 31, v20
	v_lshlrev_b32_e32 v26, 3, v25
	v_mul_f32_e32 v5, 0x45800000, v4
	v_cndmask_b32_e32 v40, v4, v5, vcc
	v_pk_mul_f32 v[4:5], v[40:41], v[30:31] op_sel_hi:[0,1]
	v_pk_mul_f32 v[6:7], v[40:41], v[12:13] op_sel_hi:[0,1]
	s_waitcnt vmcnt(0)
	v_pk_mul_f32 v[4:5], v[16:17], v[4:5]
	v_pk_mul_f32 v[6:7], v[18:19], v[6:7]
	v_pk_mul_f32 v[4:5], v[28:29], v[4:5]
	v_pk_mul_f32 v[6:7], v[32:33], v[6:7]
	v_cvt_pk_bf16_f32 v4, v4, v5
	v_cvt_pk_bf16_f32 v5, v6, v7
	v_pk_mul_f32 v[6:7], v[40:41], v[36:37] op_sel_hi:[0,1]
	v_pk_mul_f32 v[0:1], v[0:1], v[6:7]
	v_ashrrev_i32_e32 v27, 31, v26
	v_pk_mul_f32 v[0:1], v[34:35], v[0:1]
	v_lshl_add_u64 v[16:17], v[26:27], 2, s[18:19]
	v_cvt_pk_bf16_f32 v6, v0, v1
	v_pk_mul_f32 v[0:1], v[40:41], v[14:15] op_sel_hi:[0,1]
	v_pk_mul_f32 v[0:1], v[2:3], v[0:1]
	s_nop 0
	v_pk_mul_f32 v[0:1], v[38:39], v[0:1]
	s_nop 0
	v_cvt_pk_bf16_f32 v7, v0, v1
	v_lshl_add_u64 v[0:1], s[12:13], 0, v[20:21]
	v_mad_u64_u32 v[2:3], s[6:7], v0, s70, v[8:9]
	global_store_dwordx4 v[22:23], v[4:7], off sc1
	v_mul_f32_e32 v21, 0x4b800000, v24
	v_mul_lo_u32 v20, v20, s79
	v_mov_b32_e32 v4, v3
	v_mad_u64_u32 v[4:5], s[6:7], v1, s70, v[4:5]
	v_mov_b32_e32 v3, v4
	v_lshl_add_u64 v[2:3], v[2:3], 0, s[56:57]
	v_lshlrev_b64 v[6:7], 1, v[26:27]
	v_lshl_add_u64 v[2:3], v[2:3], 0, v[6:7]
	v_add_co_u32_e32 v2, vcc, s80, v2
	v_lshlrev_b64 v[0:1], 12, v[0:1]
	s_nop 0
	v_addc_co_u32_e32 v3, vcc, 0, v3, vcc
	global_load_dwordx4 v[2:5], v[2:3], off offset:3072
	s_nop 0
	global_load_dwordx4 v[12:15], v[16:17], off
	s_nop 0
	global_load_dwordx4 v[16:19], v[16:17], off offset:16
	v_cmp_gt_f32_e32 vcc, s81, v24
	v_lshl_add_u64 v[0:1], s[16:17], 0, v[0:1]
	v_lshl_add_u64 v[0:1], v[0:1], 0, v[6:7]
	v_cndmask_b32_e32 v21, v24, v21, vcc
	v_rsq_f32_e32 v26, v21
	v_lshlrev_b32_e32 v21, 4, v25
	v_add3_u32 v20, v42, v20, v21
	ds_read_b128 v[20:23], v20 offset:63488
	v_mul_f32_e32 v28, 0x45800000, v26
	v_cndmask_b32_e32 v26, v26, v28, vcc
	s_waitcnt lgkmcnt(0)
	v_lshlrev_b32_e32 v28, 16, v20
	v_and_b32_e32 v29, 0xffff0000, v20
	s_waitcnt vmcnt(2)
	v_lshlrev_b32_e32 v27, 16, v2
	v_and_b32_e32 v2, 0xffff0000, v2
	v_mul_f32_e32 v24, 0xbfb8aa3b, v27
	v_mul_f32_e32 v25, 0xbfb8aa3b, v2
	v_exp_f32_e32 v24, v24
	v_exp_f32_e32 v25, v25
	v_pk_mul_f32 v[28:29], v[26:27], v[28:29] op_sel_hi:[0,1]
	s_waitcnt vmcnt(1)
	v_pk_mul_f32 v[12:13], v[12:13], v[28:29]
	v_pk_add_f32 v[24:25], v[24:25], 1.0 op_sel_hi:[1,0]
	s_nop 0
	s_nop 0
	v_rcp_f32_e32 v20, v25
	s_nop 0
	v_mul_f32_e32 v25, v2, v20
	v_lshlrev_b32_e32 v20, 16, v3
	v_rcp_f32_e32 v2, v24
	s_nop 0
	v_mul_f32_e32 v24, v27, v2
	v_and_b32_e32 v27, 0xffff0000, v3
	v_mul_f32_e32 v2, 0xbfb8aa3b, v20
	v_exp_f32_e32 v28, v2
	v_mul_f32_e32 v2, 0xbfb8aa3b, v27
	v_exp_f32_e32 v29, v2
	v_pk_mul_f32 v[2:3], v[24:25], v[12:13]
	v_lshlrev_b32_e32 v12, 16, v21
	v_cvt_pk_bf16_f32 v2, v2, v3
	v_pk_add_f32 v[24:25], v[28:29], 1.0 op_sel_hi:[1,0]
	v_and_b32_e32 v13, 0xffff0000, v21
	v_pk_mul_f32 v[12:13], v[26:27], v[12:13] op_sel_hi:[0,1]
	v_pk_mul_f32 v[12:13], v[14:15], v[12:13]
	v_div_scale_f32 v14, s[6:7], v24, v24, v20
	v_rcp_f32_e32 v21, v14
	v_rcp_f32_e32 v3, v25
	s_nop 0
	v_mul_f32_e32 v15, v27, v3
	v_fma_f32 v3, -v14, v21, 1.0
	v_fmac_f32_e32 v21, v3, v21
	v_div_scale_f32 v3, vcc, v20, v24, v20
	v_mul_f32_e32 v25, v3, v21
	v_fma_f32 v27, -v14, v25, v3
	v_rcp_f32_e32 v3, v24
	s_nop 0
	v_mul_f32_e32 v14, v20, v3
	v_lshlrev_b32_e32 v24, 16, v4
	v_and_b32_e32 v4, 0xffff0000, v4
	v_mul_f32_e32 v3, 0xbfb8aa3b, v24
	v_exp_f32_e32 v20, v3
	v_mul_f32_e32 v3, 0xbfb8aa3b, v4
	v_exp_f32_e32 v21, v3
	v_pk_mul_f32 v[12:13], v[14:15], v[12:13]
	v_pk_add_f32 v[14:15], v[20:21], 1.0 op_sel_hi:[1,0]
	s_nop 0
	v_cvt_pk_bf16_f32 v3, v12, v13
	v_lshlrev_b32_e32 v12, 16, v22
	v_and_b32_e32 v13, 0xffff0000, v22
	v_pk_mul_f32 v[12:13], v[26:27], v[12:13] op_sel_hi:[0,1]
	s_waitcnt vmcnt(0)
	v_pk_mul_f32 v[12:13], v[16:17], v[12:13]
	v_rcp_f32_e32 v16, v15
	s_nop 0
	v_mul_f32_e32 v15, v4, v16
	v_and_b32_e32 v21, 0xffff0000, v5
	v_lshlrev_b32_e32 v20, 16, v5
	v_rcp_f32_e32 v4, v14
	s_nop 0
	v_mul_f32_e32 v14, v24, v4
	v_mul_f32_e32 v4, 0xbfb8aa3b, v20
	v_exp_f32_e32 v16, v4
	v_mul_f32_e32 v4, 0xbfb8aa3b, v21
	v_exp_f32_e32 v17, v4
	v_pk_mul_f32 v[4:5], v[14:15], v[12:13]
	v_lshlrev_b32_e32 v12, 16, v23
	v_cvt_pk_bf16_f32 v4, v4, v5
	v_pk_add_f32 v[14:15], v[16:17], 1.0 op_sel_hi:[1,0]
	v_and_b32_e32 v13, 0xffff0000, v23
	v_pk_mul_f32 v[12:13], v[26:27], v[12:13] op_sel_hi:[0,1]
	v_pk_mul_f32 v[12:13], v[18:19], v[12:13]
	v_rcp_f32_e32 v5, v15
	s_nop 0
	v_mul_f32_e32 v15, v21, v5
	v_rcp_f32_e32 v5, v14
	s_nop 0
	v_mul_f32_e32 v14, v20, v5
	v_pk_mul_f32 v[12:13], v[14:15], v[12:13]
	s_nop 0
	v_cvt_pk_bf16_f32 v5, v12, v13
	global_store_dwordx4 v[0:1], v[2:5], off sc1
	v_add_u32_e32 v1, 0x800, v230
	v_mul_hi_i32 v0, v1, s74
	v_lshrrev_b32_e32 v2, 31, v0
	v_ashrrev_i32_e32 v0, 3, v0
	v_add_u32_e32 v0, v0, v2
	v_mul_lo_u32 v2, v0, 48
	v_sub_u32_e32 v12, v1, v2
	v_ashrrev_i32_e32 v1, 31, v0
	v_lshl_add_u64 v[20:21], s[12:13], 0, v[0:1]
	v_mad_u64_u32 v[4:5], s[6:7], v20, s70, v[8:9]
	v_mov_b32_e32 v6, v5
	v_lshlrev_b32_e32 v2, 3, v12
	v_mad_u64_u32 v[6:7], s[6:7], v21, s70, v[6:7]
	v_mov_b32_e32 v5, v6
	v_ashrrev_i32_e32 v3, 31, v2
	v_lshl_add_u64 v[4:5], v[4:5], 0, s[56:57]
	v_lshlrev_b64 v[22:23], 1, v[2:3]
	v_lshl_add_u64 v[4:5], v[4:5], 0, v[22:23]
	v_add_co_u32_e32 v4, vcc, s80, v4
	v_lshl_add_u32 v13, v0, 2, 0
	s_nop 0
	v_addc_co_u32_e32 v5, vcc, 0, v5, vcc
	global_load_dwordx4 v[4:7], v[4:5], off offset:3072
	v_mul_lo_u32 v14, v0, s79
	v_lshlrev_b32_e32 v12, 4, v12
	v_add3_u32 v12, v13, v14, v12
	ds_read2st64_b32 v[24:25], v13 offset0:16 offset1:17
	ds_read2st64_b32 v[26:27], v13 offset0:18 offset1:19
	ds_read_b128 v[12:15], v12 offset:63488
	v_lshl_add_u64 v[16:17], v[2:3], 2, s[18:19]
	s_waitcnt lgkmcnt(0)
	v_lshlrev_b32_e32 v30, 16, v12
	v_and_b32_e32 v31, 0xffff0000, v12
	s_waitcnt vmcnt(0)
	v_lshlrev_b32_e32 v32, 16, v4
	v_and_b32_e32 v4, 0xffff0000, v4
	v_mul_f32_e32 v0, 0xbfb8aa3b, v32
	v_mul_f32_e32 v1, 0xbfb8aa3b, v4
	v_exp_f32_e32 v0, v0
	v_exp_f32_e32 v1, v1
	v_lshlrev_b32_e32 v37, 16, v5
	v_lshlrev_b32_e32 v40, 16, v6
	v_and_b32_e32 v6, 0xffff0000, v6
	v_pk_add_f32 v[28:29], v[0:1], 1.0 op_sel_hi:[1,0]
	global_load_dwordx4 v[0:3], v[16:17], off offset:16
	s_nop 0
	global_load_dwordx4 v[16:19], v[16:17], off
	v_lshlrev_b32_e32 v41, 16, v7
	v_and_b32_e32 v7, 0xffff0000, v7
	v_rcp_f32_e32 v12, v29
	s_nop 0
	v_mul_f32_e32 v29, v4, v12
	v_and_b32_e32 v35, 0xffff0000, v5
	v_mul_f32_e32 v4, 0xbfb8aa3b, v37
	v_mul_f32_e32 v5, 0xbfb8aa3b, v35
	v_exp_f32_e32 v4, v4
	v_exp_f32_e32 v5, v5
	v_rcp_f32_e32 v12, v28
	s_nop 0
	v_mul_f32_e32 v28, v32, v12
	v_pk_add_f32 v[4:5], v[4:5], 1.0 op_sel_hi:[1,0]
	v_lshlrev_b32_e32 v12, 16, v13
	v_and_b32_e32 v13, 0xffff0000, v13
	v_rcp_f32_e32 v32, v5
	s_nop 0
	v_mul_f32_e32 v33, v35, v32
	v_mul_f32_e32 v34, 0xbfb8aa3b, v40
	v_mul_f32_e32 v35, 0xbfb8aa3b, v6
	v_exp_f32_e32 v34, v34
	v_exp_f32_e32 v35, v35
	v_rcp_f32_e32 v5, v4
	s_nop 0
	v_mul_f32_e32 v32, v37, v5
	v_pk_add_f32 v[34:35], v[34:35], 1.0 op_sel_hi:[1,0]
	v_lshlrev_b32_e32 v36, 16, v14
	v_and_b32_e32 v37, 0xffff0000, v14
	v_rcp_f32_e32 v4, v35
	s_nop 0
	v_mul_f32_e32 v35, v6, v4
	v_mul_f32_e32 v4, 0xbfb8aa3b, v41
	v_mul_f32_e32 v5, 0xbfb8aa3b, v7
	v_exp_f32_e32 v4, v4
	v_exp_f32_e32 v5, v5
	v_rcp_f32_e32 v6, v34
	s_nop 0
	v_mul_f32_e32 v34, v40, v6
	v_pk_add_f32 v[4:5], v[4:5], 1.0 op_sel_hi:[1,0]
	v_lshlrev_b32_e32 v14, 16, v15
	v_and_b32_e32 v15, 0xffff0000, v15
	v_rcp_f32_e32 v6, v5
	s_nop 0
	v_mul_f32_e32 v39, v7, v6
	v_div_scale_f32 v5, vcc, v41, v4, v41
	v_rcp_f32_e32 v5, v4
	s_nop 0
	v_mul_f32_e32 v38, v41, v5
	v_lshlrev_b64 v[4:5], 12, v[20:21]
	v_add_u32_e32 v21, 0xa00, v230
	v_mul_hi_i32 v6, v21, s74
	v_lshrrev_b32_e32 v7, 31, v6
	v_ashrrev_i32_e32 v6, 3, v6
	v_add_u32_e32 v20, v6, v7
	v_lshl_add_u32 v42, v20, 2, 0
	ds_read2st64_b32 v[6:7], v42 offset0:16 offset1:17
	v_lshl_add_u64 v[4:5], s[16:17], 0, v[4:5]
	v_lshl_add_u64 v[22:23], v[4:5], 0, v[22:23]
	ds_read2st64_b32 v[4:5], v42 offset0:18 offset1:19
	v_mov_b32_e32 v41, v24
	s_waitcnt lgkmcnt(1)
	v_mov_b32_e32 v40, v6
	v_mov_b32_e32 v24, v7
	v_pk_add_f32 v[6:7], v[40:41], v[24:25]
	s_waitcnt lgkmcnt(0)
	v_mov_b32_e32 v24, v4
	v_mov_b32_e32 v25, v26
	v_pk_add_f32 v[6:7], v[6:7], v[24:25]
	v_mov_b32_e32 v26, v5
	v_pk_add_f32 v[4:5], v[6:7], v[26:27]
	v_mul_lo_u32 v43, v20, 48
	v_pk_fma_f32 v[24:25], v[4:5], s[64:65], v[10:11] op_sel_hi:[1,0,0]
	s_nop 0
	v_mul_f32_e32 v4, 0x4b800000, v25
	v_cmp_gt_f32_e32 vcc, s81, v25
	s_nop 1
	v_cndmask_b32_e32 v4, v25, v4, vcc
	v_rsq_f32_e32 v4, v4
	v_sub_u32_e32 v25, v21, v43
	v_ashrrev_i32_e32 v21, 31, v20
	v_lshlrev_b32_e32 v10, 3, v25
	v_mul_f32_e32 v5, 0x45800000, v4
	v_cndmask_b32_e32 v26, v4, v5, vcc
	v_pk_mul_f32 v[4:5], v[26:27], v[30:31] op_sel_hi:[0,1]
	v_pk_mul_f32 v[6:7], v[26:27], v[12:13] op_sel_hi:[0,1]
	s_waitcnt vmcnt(0)
	v_pk_mul_f32 v[4:5], v[16:17], v[4:5]
	v_pk_mul_f32 v[6:7], v[18:19], v[6:7]
	v_pk_mul_f32 v[4:5], v[28:29], v[4:5]
	v_pk_mul_f32 v[6:7], v[32:33], v[6:7]
	v_cvt_pk_bf16_f32 v4, v4, v5
	v_cvt_pk_bf16_f32 v5, v6, v7
	v_pk_mul_f32 v[6:7], v[26:27], v[36:37] op_sel_hi:[0,1]
	v_pk_mul_f32 v[0:1], v[0:1], v[6:7]
	v_ashrrev_i32_e32 v11, 31, v10
	v_pk_mul_f32 v[0:1], v[34:35], v[0:1]
	v_lshlrev_b64 v[18:19], 1, v[10:11]
	v_cvt_pk_bf16_f32 v6, v0, v1
	v_pk_mul_f32 v[0:1], v[26:27], v[14:15] op_sel_hi:[0,1]
	v_pk_mul_f32 v[0:1], v[2:3], v[0:1]
	v_lshl_add_u64 v[10:11], v[10:11], 2, s[18:19]
	v_pk_mul_f32 v[0:1], v[38:39], v[0:1]
	v_mul_f32_e32 v14, 0x4b800000, v24
	v_cvt_pk_bf16_f32 v7, v0, v1
	v_lshl_add_u64 v[0:1], s[12:13], 0, v[20:21]
	v_mad_u64_u32 v[2:3], s[6:7], v0, s70, v[8:9]
	global_store_dwordx4 v[22:23], v[4:7], off sc1
	v_lshlrev_b32_e32 v15, 4, v25
	s_nop 0
	v_mov_b32_e32 v4, v3
	v_mad_u64_u32 v[4:5], s[6:7], v1, s70, v[4:5]
	v_mov_b32_e32 v3, v4
	v_lshl_add_u64 v[2:3], v[2:3], 0, s[56:57]
	v_lshl_add_u64 v[2:3], v[2:3], 0, v[18:19]
	v_add_co_u32_e32 v2, vcc, s80, v2
	v_lshlrev_b64 v[0:1], 12, v[0:1]
	s_nop 0
	v_addc_co_u32_e32 v3, vcc, 0, v3, vcc
	global_load_dwordx4 v[2:5], v[2:3], off offset:3072
	s_nop 0
	global_load_dwordx4 v[6:9], v[10:11], off
	s_nop 0
	global_load_dwordx4 v[10:13], v[10:11], off offset:16
	v_cmp_gt_f32_e32 vcc, s81, v24
	v_lshl_add_u64 v[0:1], s[16:17], 0, v[0:1]
	v_lshl_add_u64 v[0:1], v[0:1], 0, v[18:19]
	v_cndmask_b32_e32 v14, v24, v14, vcc
	v_rsq_f32_e32 v22, v14
	v_mul_lo_u32 v14, v20, s79
	v_add3_u32 v14, v42, v14, v15
	ds_read_b128 v[14:17], v14 offset:63488
	v_mul_f32_e32 v24, 0x45800000, v22
	v_cndmask_b32_e32 v22, v22, v24, vcc
	s_waitcnt lgkmcnt(0)
	v_lshlrev_b32_e32 v24, 16, v14
	v_and_b32_e32 v25, 0xffff0000, v14
	s_waitcnt vmcnt(2)
	v_lshlrev_b32_e32 v23, 16, v2
	v_and_b32_e32 v2, 0xffff0000, v2
	v_mul_f32_e32 v20, 0xbfb8aa3b, v23
	v_mul_f32_e32 v21, 0xbfb8aa3b, v2
	v_exp_f32_e32 v20, v20
	v_exp_f32_e32 v21, v21
	v_pk_mul_f32 v[24:25], v[22:23], v[24:25] op_sel_hi:[0,1]
	s_waitcnt vmcnt(1)
	v_pk_mul_f32 v[6:7], v[6:7], v[24:25]
	v_pk_add_f32 v[20:21], v[20:21], 1.0 op_sel_hi:[1,0]
	s_nop 0
	v_div_scale_f32 v26, s[6:7], v21, v21, v2
	v_rcp_f32_e32 v27, v26
	s_nop 0
	v_fma_f32 v14, -v26, v27, 1.0
	v_fmac_f32_e32 v27, v14, v27
	v_div_scale_f32 v25, s[6:7], v20, v20, v23
	v_rcp_f32_e32 v26, v25
	v_rcp_f32_e32 v14, v21
	s_nop 0
	v_mul_f32_e32 v21, v2, v14
	v_fma_f32 v2, -v25, v26, 1.0
	v_fmac_f32_e32 v26, v2, v26
	v_lshlrev_b32_e32 v14, 16, v3
	v_rcp_f32_e32 v2, v20
	s_nop 0
	v_mul_f32_e32 v20, v23, v2
	v_and_b32_e32 v23, 0xffff0000, v3
	v_mul_f32_e32 v2, 0xbfb8aa3b, v14
	v_exp_f32_e32 v24, v2
	v_mul_f32_e32 v2, 0xbfb8aa3b, v23
	v_exp_f32_e32 v25, v2
	v_pk_mul_f32 v[2:3], v[20:21], v[6:7]
	v_lshlrev_b32_e32 v6, 16, v15
	v_cvt_pk_bf16_f32 v2, v2, v3
	v_pk_add_f32 v[20:21], v[24:25], 1.0 op_sel_hi:[1,0]
	v_and_b32_e32 v7, 0xffff0000, v15
	v_div_scale_f32 v3, s[6:7], v21, v21, v23
	v_rcp_f32_e32 v24, v3
	v_pk_mul_f32 v[6:7], v[22:23], v[6:7] op_sel_hi:[0,1]
	v_pk_mul_f32 v[6:7], v[8:9], v[6:7]
	v_fma_f32 v8, -v3, v24, 1.0
	v_fmac_f32_e32 v24, v8, v24
	v_div_scale_f32 v8, s[6:7], v20, v20, v14
	v_rcp_f32_e32 v15, v8
	v_rcp_f32_e32 v3, v21
	s_nop 0
	v_mul_f32_e32 v9, v23, v3
	v_fma_f32 v3, -v8, v15, 1.0
	v_fmac_f32_e32 v15, v3, v15
	v_div_scale_f32 v3, vcc, v14, v20, v14
	v_mul_f32_e32 v21, v3, v15
	v_fma_f32 v23, -v8, v21, v3
	v_fmac_f32_e32 v21, v23, v15
	v_rcp_f32_e32 v3, v20
	s_nop 0
	v_mul_f32_e32 v8, v14, v3
	v_lshlrev_b32_e32 v20, 16, v4
	v_and_b32_e32 v4, 0xffff0000, v4
	v_mul_f32_e32 v3, 0xbfb8aa3b, v20
	v_exp_f32_e32 v14, v3
	v_mul_f32_e32 v3, 0xbfb8aa3b, v4
	v_exp_f32_e32 v15, v3
	v_pk_mul_f32 v[6:7], v[8:9], v[6:7]
	v_pk_add_f32 v[8:9], v[14:15], 1.0 op_sel_hi:[1,0]
	s_nop 0
	v_cvt_pk_bf16_f32 v3, v6, v7
	v_lshlrev_b32_e32 v6, 16, v16
	v_and_b32_e32 v7, 0xffff0000, v16
	v_pk_mul_f32 v[6:7], v[22:23], v[6:7] op_sel_hi:[0,1]
	s_waitcnt vmcnt(0)
	v_pk_mul_f32 v[6:7], v[10:11], v[6:7]
	v_div_scale_f32 v14, s[6:7], v8, v8, v20
	v_rcp_f32_e32 v16, v14
	v_rcp_f32_e32 v10, v9
	s_nop 0
	v_mul_f32_e32 v9, v4, v10
	v_and_b32_e32 v15, 0xffff0000, v5
	v_fma_f32 v4, -v14, v16, 1.0
	v_fmac_f32_e32 v16, v4, v16
	v_lshlrev_b32_e32 v14, 16, v5
	v_rcp_f32_e32 v4, v8
	s_nop 0
	v_mul_f32_e32 v8, v20, v4
	v_mul_f32_e32 v4, 0xbfb8aa3b, v14
	v_exp_f32_e32 v10, v4
	v_mul_f32_e32 v4, 0xbfb8aa3b, v15
	v_exp_f32_e32 v11, v4
	v_pk_mul_f32 v[4:5], v[8:9], v[6:7]
	v_lshlrev_b32_e32 v6, 16, v17
	v_cvt_pk_bf16_f32 v4, v4, v5
	v_pk_add_f32 v[8:9], v[10:11], 1.0 op_sel_hi:[1,0]
	v_and_b32_e32 v7, 0xffff0000, v17
	v_pk_mul_f32 v[6:7], v[22:23], v[6:7] op_sel_hi:[0,1]
	v_pk_mul_f32 v[6:7], v[12:13], v[6:7]
	v_div_scale_f32 v11, s[6:7], v8, v8, v14
	v_rcp_f32_e32 v13, v11
	v_rcp_f32_e32 v5, v9
	s_nop 0
	v_mul_f32_e32 v9, v15, v5
	v_fma_f32 v5, -v11, v13, 1.0
	v_fmac_f32_e32 v13, v5, v13
	v_div_scale_f32 v5, vcc, v14, v8, v14
	v_mul_f32_e32 v10, v5, v13
	v_fma_f32 v12, -v11, v10, v5
	v_fmac_f32_e32 v10, v12, v13
	v_rcp_f32_e32 v5, v8
	s_nop 0
	v_mul_f32_e32 v8, v14, v5
	v_pk_mul_f32 v[6:7], v[8:9], v[6:7]
	s_andn2_b64 vcc, exec, s[14:15]
	v_cvt_pk_bf16_f32 v5, v6, v7
	global_store_dwordx4 v[0:1], v[2:5], off sc1
	s_barrier
	s_cbranch_vccz .LBB0_628

.LBB0_612:
	s_ashr_i32 s8, s82, 8
	s_ashr_i32 s9, s8, 31
	s_and_b32 s10, s3, 0xfc0
	s_mul_i32 s12, s82, 0x24000
	s_mul_hi_i32 s11, s82, 0x24000
	s_add_u32 s14, s65, s12
	v_and_b32_e32 v241, 63, v230
	v_cvt_pk_bf16_f32 v168, v0, v1
	v_cvt_pk_bf16_f32 v169, v2, v3
	v_cvt_pk_bf16_f32 v170, v4, v5
	v_cvt_pk_bf16_f32 v171, v6, v7
	v_cvt_pk_bf16_f32 v164, v8, v9
	v_cvt_pk_bf16_f32 v165, v10, v11
	v_cvt_pk_bf16_f32 v166, v12, v13
	v_cvt_pk_bf16_f32 v167, v14, v15
	s_addc_u32 s15, s67, s11
	s_lshl_b64 s[12:13], s[8:9], 12
	s_and_b32 s16, s82, 3
	v_cvt_pk_bf16_f32 v172, v172, v17
	v_cvt_pk_bf16_f32 v173, v18, v19
	v_cvt_pk_bf16_f32 v174, v20, v21
	v_cvt_pk_bf16_f32 v175, v22, v23
	s_ashr_i32 s17, s56, 7
	s_mul_i32 s18, s17, 0x900
	s_add_i32 s8, s18, 0x300
	v_or_b32_e32 v0, s8, v241
	v_ashrrev_i32_e32 v1, 31, v0
	v_lshl_add_u64 v[16:17], v[0:1], 4, s[14:15]
	v_mfma_f32_32x32x16_bf16 v[0:15], v[48:51], v[32:35], 0
	s_add_i32 s8, s18, 0x340
	v_or_b32_e32 v18, s8, v241
	s_add_i32 s8, s18, 0x380
	v_ashrrev_i32_e32 v19, 31, v18
	v_or_b32_e32 v20, s8, v241
	v_lshl_add_u64 v[18:19], v[18:19], 4, s[14:15]
	v_ashrrev_i32_e32 v21, 31, v20
	v_mfma_f32_32x32x16_bf16 v[0:15], v[52:55], v[120:123], v[0:15]
	s_add_i32 s8, s18, 0x3c0
	v_lshl_add_u64 v[20:21], v[20:21], 4, s[14:15]
	global_load_dwordx4 v[40:43], v[18:19], off
	global_load_dwordx4 v[36:39], v[20:21], off
	v_or_b32_e32 v18, s8, v241
	s_add_i32 s8, s18, 0x400
	v_ashrrev_i32_e32 v19, 31, v18
	v_or_b32_e32 v20, s8, v241
	v_mfma_f32_32x32x16_bf16 v[0:15], v[56:59], v[128:131], v[0:15]
	v_lshl_add_u64 v[18:19], v[18:19], 4, s[14:15]
	v_ashrrev_i32_e32 v21, 31, v20
	s_add_i32 s8, s18, 0x440
	v_lshl_add_u64 v[20:21], v[20:21], 4, s[14:15]
	global_load_dwordx4 v[176:179], v[18:19], off
	global_load_dwordx4 v[44:47], v[20:21], off
	v_or_b32_e32 v18, s8, v241
	s_add_i32 s8, s18, 0x480
	v_mfma_f32_32x32x16_bf16 v[0:15], v[60:63], v[124:127], v[0:15]
	v_ashrrev_i32_e32 v19, 31, v18
	v_or_b32_e32 v20, s8, v241
	v_lshl_add_u64 v[18:19], v[18:19], 4, s[14:15]
	v_ashrrev_i32_e32 v21, 31, v20
	s_add_i32 s8, s18, 0x4c0
	v_lshl_add_u64 v[20:21], v[20:21], 4, s[14:15]
	global_load_dwordx4 v[184:187], v[18:19], off
	global_load_dwordx4 v[180:183], v[20:21], off
	v_mfma_f32_32x32x16_bf16 v[0:15], v[64:67], v[136:139], v[0:15]
	v_or_b32_e32 v18, s8, v241
	s_add_i32 s8, s18, 0x500
	v_or_b32_e32 v20, s8, v241
	s_mul_i32 s8, s17, 3
	s_mul_i32 s9, s16, 12
	s_add_i32 s8, s8, s9
	v_lshlrev_b32_e32 v216, 4, v241
	v_mfma_f32_32x32x16_bf16 v[0:15], v[68:71], v[132:135], v[0:15]
	s_ashr_i32 s9, s8, 31
	s_or_b32 s12, s12, s10
	v_lshl_add_u64 v[224:225], s[58:59], 0, v[216:217]
	s_lshl_b64 s[20:21], s[8:9], 20
	v_ashrrev_i32_e32 v19, 31, v18
	s_lshl_b64 s[10:11], s[12:13], 6
	v_lshl_add_u64 v[22:23], v[224:225], 0, s[20:21]
	v_mfma_f32_32x32x16_bf16 v[0:15], v[72:75], v[144:147], v[0:15]
	v_lshl_add_u64 v[18:19], v[18:19], 4, s[14:15]
	v_ashrrev_i32_e32 v21, 31, v20
	v_lshl_add_u64 v[24:25], v[22:23], 0, s[10:11]
	s_add_i32 s19, s18, 0x540
	v_lshl_add_u64 v[20:21], v[20:21], 4, s[14:15]
	global_load_dwordx4 v[244:247], v[24:25], off
	global_load_dwordx4 v[200:203], v[18:19], off
	global_load_dwordx4 v[192:195], v[20:21], off
	v_mfma_f32_32x32x16_bf16 v[0:15], v[76:79], v[140:143], v[0:15]
	v_or_b32_e32 v18, s19, v241
	s_add_i32 s19, s18, 0x580
	v_ashrrev_i32_e32 v19, 31, v18
	v_or_b32_e32 v20, s19, v241
	v_lshl_add_u64 v[18:19], v[18:19], 4, s[14:15]
	v_ashrrev_i32_e32 v21, 31, v20
	s_add_i32 s19, s18, 0x5c0
	v_lshl_add_u64 v[20:21], v[20:21], 4, s[14:15]
	global_load_dwordx4 v[204:207], v[18:19], off
	global_load_dwordx4 v[196:199], v[20:21], off
	v_or_b32_e32 v18, s19, v241
	s_add_i32 s19, s18, 0x600
	v_or_b32_e32 v48, s19, v241
	v_ashrrev_i32_e32 v19, 31, v18
	v_ashrrev_i32_e32 v49, 31, v48
	v_mfma_f32_32x32x16_bf16 v[0:15], v[84:87], v[152:155], v[0:15]
	v_lshl_add_u64 v[30:31], v[18:19], 4, s[14:15]
	v_lshl_add_u64 v[48:49], v[48:49], 4, s[14:15]
	s_add_i32 s19, s18, 0x640
	global_load_dwordx4 v[248:251], v[24:25], off offset:1024
	s_nop 0
	global_load_dwordx4 v[16:19], v[16:17], off
	s_nop 0
	global_load_dwordx4 v[20:23], v[24:25], off offset:3072
	global_load_dwordx4 v[208:211], v[30:31], off
	s_nop 0
	global_load_dwordx4 v[48:51], v[48:49], off
	v_or_b32_e32 v30, s19, v241
	s_add_i32 s19, s18, 0x680
	v_or_b32_e32 v52, s19, v241
	v_ashrrev_i32_e32 v31, 31, v30
	v_ashrrev_i32_e32 v53, 31, v52
	v_lshl_add_u64 v[30:31], v[30:31], 4, s[14:15]
	v_lshl_add_u64 v[56:57], v[52:53], 4, s[14:15]
	s_add_i32 s19, s18, 0x6c0
	global_load_dwordx4 v[52:55], v[30:31], off
	s_nop 0
	global_load_dwordx4 v[56:59], v[56:57], off
	v_or_b32_e32 v30, s19, v241
	s_add_i32 s19, s18, 0x700
	v_or_b32_e32 v60, s19, v241
	v_ashrrev_i32_e32 v31, 31, v30
	v_ashrrev_i32_e32 v61, 31, v60
	v_mfma_f32_32x32x16_bf16 v[0:15], v[92:95], v[148:151], v[0:15]
	v_lshl_add_u64 v[30:31], v[30:31], 4, s[14:15]
	v_lshl_add_u64 v[64:65], v[60:61], 4, s[14:15]
	s_add_i32 s19, s18, 0x740
	global_load_dwordx4 v[60:63], v[30:31], off
	s_nop 0
	global_load_dwordx4 v[64:67], v[64:65], off
	v_or_b32_e32 v30, s19, v241
	s_add_i32 s19, s18, 0x780
	v_or_b32_e32 v68, s19, v241
	v_ashrrev_i32_e32 v31, 31, v30
	v_ashrrev_i32_e32 v69, 31, v68
	v_lshl_add_u64 v[30:31], v[30:31], 4, s[14:15]
	v_lshl_add_u64 v[72:73], v[68:69], 4, s[14:15]
	s_add_i32 s19, s18, 0x7c0
	global_load_dwordx4 v[68:71], v[30:31], off
	s_nop 0
	global_load_dwordx4 v[72:75], v[72:73], off
	v_or_b32_e32 v30, s19, v241
	s_add_i32 s19, s18, 0x800
	v_or_b32_e32 v76, s19, v241
	v_ashrrev_i32_e32 v31, 31, v30
	v_ashrrev_i32_e32 v77, 31, v76
	v_mfma_f32_32x32x16_bf16 v[0:15], v[96:99], v[156:159], v[0:15]
	v_lshl_add_u64 v[30:31], v[30:31], 4, s[14:15]
	v_lshl_add_u64 v[84:85], v[76:77], 4, s[14:15]
	s_add_i32 s19, s18, 0x840
	global_load_dwordx4 v[76:79], v[30:31], off
	s_nop 0
	global_load_dwordx4 v[84:87], v[84:85], off
	v_or_b32_e32 v30, s19, v241
	s_add_i32 s19, s18, 0x880
	v_or_b32_e32 v92, s19, v241
	v_ashrrev_i32_e32 v31, 31, v30
	v_ashrrev_i32_e32 v93, 31, v92
	v_lshl_add_u64 v[30:31], v[30:31], 4, s[14:15]
	v_lshl_add_u64 v[96:97], v[92:93], 4, s[14:15]
	s_addk_i32 s18, 0x8c0
	global_load_dwordx4 v[92:95], v[30:31], off
	s_nop 0
	global_load_dwordx4 v[96:99], v[96:97], off
	v_or_b32_e32 v30, s18, v241
	v_ashrrev_i32_e32 v31, 31, v30
	v_lshl_add_u64 v[30:31], v[30:31], 4, s[14:15]
	v_mfma_f32_32x32x16_bf16 v[0:15], v[100:103], v[160:163], v[0:15]
	global_load_dwordx4 v[100:103], v[30:31], off
	s_and_b64 vcc, exec, s[6:7]
	s_waitcnt vmcnt(20)
	v_mfma_f32_32x32x16_bf16 v[0:15], v[244:247], v[168:171], v[0:15]
	s_waitcnt vmcnt(15)
	v_mfma_f32_32x32x16_bf16 v[0:15], v[248:251], v[164:167], v[0:15]
	s_cbranch_vccnz .LBB0_614
	global_load_dwordx4 v[244:247], v[24:25], off offset:2048
	s_waitcnt vmcnt(0)
	v_mfma_f32_32x32x16_bf16 v[0:15], v[244:247], v[172:175], v[0:15]

.LBB0_624:
	s_add_i32 s82, s82, s46
	s_cmpk_gt_i32 s82, 0x3ff
	s_waitcnt vmcnt(0)
	s_nop 8
	v_cvt_pk_bf16_f32 v120, v32, v33
	v_cvt_pk_bf16_f32 v121, v34, v35
	v_cvt_pk_bf16_f32 v122, v36, v37
	v_cvt_pk_bf16_f32 v123, v38, v39
	s_cselect_b64 s[14:15], -1, 0
	ds_write2_b64 v176, v[120:121], v[122:123] offset0:16 offset1:18
	v_cvt_pk_bf16_f32 v120, v40, v41
	v_cvt_pk_bf16_f32 v121, v42, v43
	v_cvt_pk_bf16_f32 v122, v44, v45
	v_cvt_pk_bf16_f32 v123, v46, v47
	s_and_b64 vcc, exec, s[14:15]
	ds_write2_b64 v176, v[120:121], v[122:123] offset0:20 offset1:22
	s_cbranch_vccnz .LBB0_626
	s_ashr_i32 s6, s82, 8
	s_ashr_i32 s7, s6, 31
	s_add_i32 s8, s73, s3
	s_lshl_b64 s[6:7], s[6:7], 12
	s_and_b32 s8, s8, 0xfc0
	s_or_b32 s6, s6, s8
	s_mul_i32 s8, s82, 0x24000
	s_mul_hi_i32 s9, s82, 0x24000
	s_add_u32 s8, s65, s8
	v_readfirstlane_b32 s10, v230
	s_addc_u32 s9, s67, s9
	s_lshr_b32 s10, s10, 7
	s_mulk_i32 s10, 0x900
	s_add_i32 s11, s10, 0x100
	v_or_b32_e32 v64, s11, v241
	s_add_i32 s11, s10, 0x140
	v_or_b32_e32 v66, s11, v241
	s_add_i32 s11, s10, 0x180
	v_or_b32_e32 v56, s10, v241
	v_or_b32_e32 v72, s11, v241
	s_add_i32 s11, s10, 0x1c0
	v_ashrrev_i32_e32 v57, 31, v56
	v_or_b32_e32 v74, s11, v241
	s_add_i32 s11, s10, 0x200
	v_lshl_add_u64 v[48:49], v[56:57], 4, s[8:9]
	v_or_b32_e32 v50, 64, v56
	v_or_b32_e32 v58, 0x80, v56
	v_or_b32_e32 v56, 0xc0, v56
	v_or_b32_e32 v80, s11, v241
	s_add_i32 s11, s10, 0x240
	v_ashrrev_i32_e32 v51, 31, v50
	v_ashrrev_i32_e32 v59, 31, v58
	v_ashrrev_i32_e32 v57, 31, v56
	v_ashrrev_i32_e32 v65, 31, v64
	v_ashrrev_i32_e32 v67, 31, v66
	v_ashrrev_i32_e32 v73, 31, v72
	v_ashrrev_i32_e32 v75, 31, v74
	v_ashrrev_i32_e32 v81, 31, v80
	v_or_b32_e32 v82, s11, v241
	v_lshl_add_u64 v[52:53], v[50:51], 4, s[8:9]
	v_lshl_add_u64 v[58:59], v[58:59], 4, s[8:9]
	v_lshl_add_u64 v[60:61], v[56:57], 4, s[8:9]
	v_lshl_add_u64 v[64:65], v[64:65], 4, s[8:9]
	v_lshl_add_u64 v[68:69], v[66:67], 4, s[8:9]
	v_lshl_add_u64 v[72:73], v[72:73], 4, s[8:9]
	v_lshl_add_u64 v[76:77], v[74:75], 4, s[8:9]
	v_lshl_add_u64 v[80:81], v[80:81], 4, s[8:9]
	v_ashrrev_i32_e32 v83, 31, v82
	s_add_i32 s11, s10, 0x280
	global_load_dwordx4 v[48:51], v[48:49], off
	s_nop 0
	global_load_dwordx4 v[52:55], v[52:53], off
	s_nop 0
	global_load_dwordx4 v[56:59], v[58:59], off
	s_nop 0
	global_load_dwordx4 v[60:63], v[60:61], off
	s_nop 0
	global_load_dwordx4 v[64:67], v[64:65], off
	s_nop 0
	global_load_dwordx4 v[68:71], v[68:69], off
	s_nop 0
	global_load_dwordx4 v[72:75], v[72:73], off
	s_nop 0
	global_load_dwordx4 v[76:79], v[76:77], off
	v_lshl_add_u64 v[82:83], v[82:83], 4, s[8:9]
	global_load_dwordx4 v[84:87], v[80:81], off
	global_load_dwordx4 v[92:95], v[82:83], off
	v_or_b32_e32 v80, s11, v241
	s_addk_i32 s10, 0x2c0
	v_ashrrev_i32_e32 v81, 31, v80
	v_or_b32_e32 v82, s10, v241
	v_lshl_add_u64 v[80:81], v[80:81], 4, s[8:9]
	v_ashrrev_i32_e32 v83, 31, v82
	v_ashrrev_i32_e32 v223, 31, v222
	v_lshl_add_u64 v[82:83], v[82:83], 4, s[8:9]
	global_load_dwordx4 v[96:99], v[80:81], off
	global_load_dwordx4 v[100:103], v[82:83], off
	v_lshl_add_u64 v[80:81], s[6:7], 0, v[222:223]
	v_mov_b64_e32 v[112:113], s[54:55]
	s_and_b32 s10, s82, 3
	v_mad_u64_u32 v[82:83], s[8:9], v80, s70, v[112:113]
	v_mad_i32_i24 v83, v81, s70, v83
	s_mul_i32 s56, s10, 0x180
	v_lshl_add_u64 v[80:81], v[82:83], 0, s[56:57]
	v_lshlrev_b32_e32 v82, 3, v221
	v_ashrrev_i32_e32 v221, 31, v220
	v_lshl_add_u64 v[104:105], s[6:7], 0, v[220:221]
	v_mad_u64_u32 v[106:107], s[8:9], v104, s70, v[112:113]
	v_mad_i32_i24 v107, v105, s70, v107
	v_lshl_add_u64 v[104:105], v[106:107], 0, s[56:57]
	v_lshlrev_b32_e32 v106, 3, v219
	v_ashrrev_i32_e32 v219, 31, v218
	v_lshl_add_u64 v[114:115], s[6:7], 0, v[218:219]
	v_mad_u64_u32 v[112:113], s[6:7], v114, s70, v[112:113]
	v_mad_i32_i24 v113, v115, s70, v113
	v_lshlrev_b32_e32 v114, 3, v240
	v_ashrrev_i32_e32 v83, 31, v82
	v_ashrrev_i32_e32 v107, 31, v106
	v_lshl_add_u64 v[112:113], v[112:113], 0, s[56:57]
	v_ashrrev_i32_e32 v115, 31, v114
	v_lshl_add_u64 v[88:89], v[82:83], 1, v[80:81]
	v_lshl_add_u64 v[108:109], v[106:107], 1, v[104:105]
	v_lshl_add_u64 v[116:117], v[114:115], 1, v[112:113]
	global_load_dwordx4 v[80:83], v[88:89], off offset:1536
	s_nop 0
	global_load_dwordx4 v[88:91], v[88:89], off
	s_nop 0
	global_load_dwordx4 v[104:107], v[108:109], off offset:1536
	s_nop 0
	global_load_dwordx4 v[108:111], v[108:109], off
	s_nop 0
	global_load_dwordx4 v[112:115], v[116:117], off offset:1536
	s_nop 0
	global_load_dwordx4 v[116:119], v[116:117], off
